# dwordx4 output stores of phases 1 and 11 (SwiGLU GEMM epilogues, weight copies) written through, on the lnpass-in-phase-6 version
# baseline (speedup 1.0000x reference)
; __device__ __forceinline__ unsigned pk2(float lo, float hi) { f32x2 v = {lo, hi}; bf16x2_t b = __builtin_convertvector(v, bf16x2_t); return __builtin_bit_cast(unsigned, b); }
; __device__ __forceinline__ float sigmoidf_(float x) { return frcp(1.f + fexp2(-1.4426950408889634f * x)); }
;     __device__ __forceinline__ void operator()(const f32x4 (&acc)[2][2][4][2], const Unit& u, int wr, int wc, int fr, int fq) const {
;         const int col0 = u.pn * 128 + wc * 32 + 8 * fq;
; #pragma unroll
;         for (int ai = 0; ai < 2; ++ai)
; #pragma unroll
;             for (int m = 0; m < 4; ++m) {
;                 const int row = u.pm * 256 + ai * 128 + wr * 64 + m * 16 + fr;
;                 float v[8];
; #pragma unroll
;                 for (int n = 0; n < 2; ++n)
; #pragma unroll
;                     for (int i = 0; i < 4; ++i) { const float g = acc[ai][0][m][n][i], up = acc[ai][1][m][n][i]; v[n * 4 + i] = g * sigmoidf_(g) * up; }
;                 u32x4 w; w.x = pk2(v[0], v[1]); w.y = pk2(v[2], v[3]); w.z = pk2(v[4], v[5]); w.w = pk2(v[6], v[7]);
;                 if (row < MR) *(u32x4*)(O + (size_t)row * DFF + col0) = w;
;                 asm volatile("" ::: "memory");
;             }
;     }
.LBB0_152:
	s_lshl_b32 s15, s22, 8
	v_lshl_or_b32 v144, s24, 7, v152
	v_add_u32_e32 v156, s15, v147
	v_ashrrev_i32_e32 v145, 31, v144
	v_cmp_gt_i32_e32 vcc, s57, v156
	s_and_saveexec_b64 s[22:23], vcc
	s_cbranch_execz .LBB0_154
	v_mul_f32_e32 v157, 0xbfb8aa3b, v124
	v_mul_f32_e32 v158, 0xbfb8aa3b, v125
	v_exp_f32_e32 v157, v157
	v_exp_f32_e32 v158, v158
	v_add_f32_e32 v157, 1.0, v157
	v_add_f32_e32 v159, 1.0, v158
	v_rcp_f32_e32 v158, v157
	v_rcp_f32_e32 v159, v159
	v_mul_f32_e32 v157, 0xbfb8aa3b, v126
	v_exp_f32_e32 v157, v157
	v_pk_mul_f32 v[124:125], v[124:125], v[158:159]
	v_mul_f32_e32 v158, 0xbfb8aa3b, v127
	v_exp_f32_e32 v158, v158
	v_pk_mul_f32 v[116:117], v[124:125], v[116:117]
	v_add_f32_e32 v124, 1.0, v157
	v_mul_f32_e32 v157, 0xbfb8aa3b, v120
	v_add_f32_e32 v125, 1.0, v158
	v_rcp_f32_e32 v124, v124
	v_rcp_f32_e32 v125, v125
	v_exp_f32_e32 v157, v157
	v_mul_f32_e32 v158, 0xbfb8aa3b, v121
	v_exp_f32_e32 v158, v158
	v_pk_mul_f32 v[124:125], v[126:127], v[124:125]
	v_add_f32_e32 v126, 1.0, v157
	v_mul_f32_e32 v157, 0xbfb8aa3b, v122
	v_add_f32_e32 v127, 1.0, v158
	v_exp_f32_e32 v157, v157
	v_mul_f32_e32 v158, 0xbfb8aa3b, v123
	v_exp_f32_e32 v159, v158
	v_rcp_f32_e32 v126, v126
	v_add_f32_e32 v157, 1.0, v157
	v_rcp_f32_e32 v127, v127
	v_rcp_f32_e32 v158, v157
	v_add_f32_e32 v157, 1.0, v159
	v_rcp_f32_e32 v159, v157
	v_pk_mul_f32 v[120:121], v[120:121], v[126:127]
	v_pk_mul_f32 v[118:119], v[124:125], v[118:119]
	v_pk_mul_f32 v[112:113], v[120:121], v[112:113]
	v_pk_mul_f32 v[120:121], v[122:123], v[158:159]
	s_nop 0
	v_pk_mul_f32 v[114:115], v[120:121], v[114:115]
	s_nop 0
	v_cvt_pk_bf16_f32 v115, v114, v115
	v_cvt_pk_bf16_f32 v114, v112, v113
	v_cvt_pk_bf16_f32 v112, v116, v117
	v_mov_b64_e32 v[116:117], s[8:9]
	v_mad_i64_i32 v[116:117], s[26:27], v156, s58, v[116:117]
	v_cvt_pk_bf16_f32 v113, v118, v119
	v_lshl_add_u64 v[116:117], v[144:145], 1, v[116:117]
	global_store_dwordx4 v[116:117], v[112:115], off sc1
.LBB0_154:
	s_or_b64 exec, exec, s[22:23]
	s_nop 0
	v_add_u32_e32 v112, s15, v149
	v_cmp_gt_i32_e32 vcc, s57, v112
	s_and_saveexec_b64 s[22:23], vcc
	s_cbranch_execz .LBB0_156
	v_mul_f32_e32 v113, 0xbfb8aa3b, v108
	v_mul_f32_e32 v114, 0xbfb8aa3b, v109
	v_exp_f32_e32 v113, v113
	v_exp_f32_e32 v114, v114
	v_add_f32_e32 v113, 1.0, v113
	v_add_f32_e32 v115, 1.0, v114
	v_rcp_f32_e32 v114, v113
	v_rcp_f32_e32 v115, v115
	v_mul_f32_e32 v113, 0xbfb8aa3b, v110
	v_exp_f32_e32 v113, v113
	v_pk_mul_f32 v[108:109], v[108:109], v[114:115]
	v_mul_f32_e32 v114, 0xbfb8aa3b, v111
	v_exp_f32_e32 v114, v114
	v_pk_mul_f32 v[100:101], v[108:109], v[100:101]
	v_add_f32_e32 v108, 1.0, v113
	v_mul_f32_e32 v113, 0xbfb8aa3b, v104
	v_add_f32_e32 v109, 1.0, v114
	v_rcp_f32_e32 v108, v108
	v_rcp_f32_e32 v109, v109
	v_exp_f32_e32 v113, v113
	v_mul_f32_e32 v114, 0xbfb8aa3b, v105
	v_exp_f32_e32 v114, v114
	v_pk_mul_f32 v[108:109], v[110:111], v[108:109]
	v_add_f32_e32 v110, 1.0, v113
	v_mul_f32_e32 v113, 0xbfb8aa3b, v106
	v_add_f32_e32 v111, 1.0, v114
	v_exp_f32_e32 v113, v113
	v_mul_f32_e32 v114, 0xbfb8aa3b, v107
	v_exp_f32_e32 v115, v114
	v_rcp_f32_e32 v110, v110
	v_add_f32_e32 v113, 1.0, v113
	v_rcp_f32_e32 v111, v111
	v_rcp_f32_e32 v114, v113
	v_add_f32_e32 v113, 1.0, v115
	v_rcp_f32_e32 v115, v113
	v_pk_mul_f32 v[104:105], v[104:105], v[110:111]
	v_pk_mul_f32 v[102:103], v[108:109], v[102:103]
	v_pk_mul_f32 v[96:97], v[104:105], v[96:97]
	v_pk_mul_f32 v[104:105], v[106:107], v[114:115]
	s_nop 0
	v_pk_mul_f32 v[98:99], v[104:105], v[98:99]
	s_nop 0
	v_cvt_pk_bf16_f32 v99, v98, v99
	v_cvt_pk_bf16_f32 v98, v96, v97
	v_cvt_pk_bf16_f32 v96, v100, v101
	v_mov_b64_e32 v[100:101], s[8:9]
	v_mad_i64_i32 v[100:101], s[26:27], v112, s58, v[100:101]
	v_cvt_pk_bf16_f32 v97, v102, v103
	v_lshl_add_u64 v[100:101], v[144:145], 1, v[100:101]
	global_store_dwordx4 v[100:101], v[96:99], off sc1
.LBB0_156:
	s_or_b64 exec, exec, s[22:23]
	s_nop 0
	v_add_u32_e32 v96, s15, v150
	v_cmp_gt_i32_e32 vcc, s57, v96
	s_and_saveexec_b64 s[22:23], vcc
	s_cbranch_execz .LBB0_158
	v_mul_f32_e32 v97, 0xbfb8aa3b, v92
	v_mul_f32_e32 v98, 0xbfb8aa3b, v93
	v_exp_f32_e32 v97, v97
	v_exp_f32_e32 v98, v98
	v_add_f32_e32 v97, 1.0, v97
	v_add_f32_e32 v99, 1.0, v98
	v_rcp_f32_e32 v98, v97
	v_rcp_f32_e32 v99, v99
	v_mul_f32_e32 v97, 0xbfb8aa3b, v94
	v_exp_f32_e32 v97, v97
	v_pk_mul_f32 v[92:93], v[92:93], v[98:99]
	v_mul_f32_e32 v98, 0xbfb8aa3b, v95
	v_exp_f32_e32 v98, v98
	v_pk_mul_f32 v[84:85], v[92:93], v[84:85]
	v_add_f32_e32 v92, 1.0, v97
	v_mul_f32_e32 v97, 0xbfb8aa3b, v88
	v_add_f32_e32 v93, 1.0, v98
	v_rcp_f32_e32 v92, v92
	v_rcp_f32_e32 v93, v93
	v_exp_f32_e32 v97, v97
	v_mul_f32_e32 v98, 0xbfb8aa3b, v89
	v_exp_f32_e32 v98, v98
	v_pk_mul_f32 v[92:93], v[94:95], v[92:93]
	v_add_f32_e32 v94, 1.0, v97
	v_mul_f32_e32 v97, 0xbfb8aa3b, v90
	v_add_f32_e32 v95, 1.0, v98
	v_exp_f32_e32 v97, v97
	v_mul_f32_e32 v98, 0xbfb8aa3b, v91
	v_exp_f32_e32 v99, v98
	v_rcp_f32_e32 v94, v94
	v_add_f32_e32 v97, 1.0, v97
	v_rcp_f32_e32 v95, v95
	v_rcp_f32_e32 v98, v97
	v_add_f32_e32 v97, 1.0, v99
	v_rcp_f32_e32 v99, v97
	v_pk_mul_f32 v[88:89], v[88:89], v[94:95]
	v_pk_mul_f32 v[86:87], v[92:93], v[86:87]
	v_pk_mul_f32 v[80:81], v[88:89], v[80:81]
	v_pk_mul_f32 v[88:89], v[90:91], v[98:99]
	s_nop 0
	v_pk_mul_f32 v[82:83], v[88:89], v[82:83]
	s_nop 0
	v_cvt_pk_bf16_f32 v83, v82, v83
	v_cvt_pk_bf16_f32 v82, v80, v81
	v_cvt_pk_bf16_f32 v80, v84, v85
	v_mov_b64_e32 v[84:85], s[8:9]
	v_mad_i64_i32 v[84:85], s[26:27], v96, s58, v[84:85]
	v_cvt_pk_bf16_f32 v81, v86, v87
	v_lshl_add_u64 v[84:85], v[144:145], 1, v[84:85]
	global_store_dwordx4 v[84:85], v[80:83], off sc1
; __device__ __forceinline__ unsigned pk2(float lo, float hi) { f32x2 v = {lo, hi}; bf16x2_t b = __builtin_convertvector(v, bf16x2_t); return __builtin_bit_cast(unsigned, b); }
; __device__ __forceinline__ float sigmoidf_(float x) { return frcp(1.f + fexp2(-1.4426950408889634f * x)); }
;     __device__ __forceinline__ void operator()(const f32x4 (&acc)[2][2][4][2], const Unit& u, int wr, int wc, int fr, int fq) const {
;         const int col0 = u.pn * 128 + wc * 32 + 8 * fq;
; #pragma unroll
;         for (int ai = 0; ai < 2; ++ai)
; #pragma unroll
;             for (int m = 0; m < 4; ++m) {
;                 const int row = u.pm * 256 + ai * 128 + wr * 64 + m * 16 + fr;
;                 float v[8];
; #pragma unroll
;                 for (int n = 0; n < 2; ++n)
; #pragma unroll
;                     for (int i = 0; i < 4; ++i) { const float g = acc[ai][0][m][n][i], up = acc[ai][1][m][n][i]; v[n * 4 + i] = g * sigmoidf_(g) * up; }
;                 u32x4 w; w.x = pk2(v[0], v[1]); w.y = pk2(v[2], v[3]); w.z = pk2(v[4], v[5]); w.w = pk2(v[6], v[7]);
;                 if (row < MR) *(u32x4*)(O + (size_t)row * DFF + col0) = w;
;                 asm volatile("" ::: "memory");
;             }
;     }
.LBB0_158:
	s_or_b64 exec, exec, s[22:23]
	s_nop 0
	v_add_u32_e32 v80, s15, v151
	v_cmp_gt_i32_e32 vcc, s57, v80
	s_and_saveexec_b64 s[22:23], vcc
	s_cbranch_execz .LBB0_160
	v_mul_f32_e32 v81, 0xbfb8aa3b, v76
	v_mul_f32_e32 v82, 0xbfb8aa3b, v77
	v_exp_f32_e32 v81, v81
	v_exp_f32_e32 v82, v82
	v_add_f32_e32 v81, 1.0, v81
	v_add_f32_e32 v83, 1.0, v82
	v_rcp_f32_e32 v82, v81
	v_rcp_f32_e32 v83, v83
	v_mul_f32_e32 v81, 0xbfb8aa3b, v78
	v_exp_f32_e32 v81, v81
	v_pk_mul_f32 v[76:77], v[76:77], v[82:83]
	v_mul_f32_e32 v82, 0xbfb8aa3b, v79
	v_exp_f32_e32 v82, v82
	v_pk_mul_f32 v[68:69], v[76:77], v[68:69]
	v_add_f32_e32 v76, 1.0, v81
	v_mul_f32_e32 v81, 0xbfb8aa3b, v72
	v_add_f32_e32 v77, 1.0, v82
	v_rcp_f32_e32 v76, v76
	v_rcp_f32_e32 v77, v77
	v_exp_f32_e32 v81, v81
	v_mul_f32_e32 v82, 0xbfb8aa3b, v73
	v_exp_f32_e32 v82, v82
	v_pk_mul_f32 v[76:77], v[78:79], v[76:77]
	v_add_f32_e32 v78, 1.0, v81
	v_mul_f32_e32 v81, 0xbfb8aa3b, v74
	v_add_f32_e32 v79, 1.0, v82
	v_exp_f32_e32 v81, v81
	v_mul_f32_e32 v82, 0xbfb8aa3b, v75
	v_exp_f32_e32 v83, v82
	v_rcp_f32_e32 v78, v78
	v_add_f32_e32 v81, 1.0, v81
	v_rcp_f32_e32 v79, v79
	v_rcp_f32_e32 v82, v81
	v_add_f32_e32 v81, 1.0, v83
	v_rcp_f32_e32 v83, v81
	v_pk_mul_f32 v[72:73], v[72:73], v[78:79]
	v_pk_mul_f32 v[70:71], v[76:77], v[70:71]
	v_pk_mul_f32 v[64:65], v[72:73], v[64:65]
	v_pk_mul_f32 v[72:73], v[74:75], v[82:83]
	s_nop 0
	v_pk_mul_f32 v[66:67], v[72:73], v[66:67]
	s_nop 0
	v_cvt_pk_bf16_f32 v67, v66, v67
	v_cvt_pk_bf16_f32 v66, v64, v65
	v_cvt_pk_bf16_f32 v64, v68, v69
	v_mov_b64_e32 v[68:69], s[8:9]
	v_mad_i64_i32 v[68:69], s[26:27], v80, s58, v[68:69]
	v_cvt_pk_bf16_f32 v65, v70, v71
	v_lshl_add_u64 v[68:69], v[144:145], 1, v[68:69]
	global_store_dwordx4 v[68:69], v[64:67], off sc1
.LBB0_160:
	s_or_b64 exec, exec, s[22:23]
	s_nop 0
	v_add_u32_e32 v64, 0x80, v156
	v_cmp_gt_i32_e32 vcc, s57, v64
	s_and_saveexec_b64 s[22:23], vcc
	s_cbranch_execz .LBB0_162
	v_mul_f32_e32 v65, 0xbfb8aa3b, v60
	v_mul_f32_e32 v66, 0xbfb8aa3b, v61
	v_exp_f32_e32 v65, v65
	v_exp_f32_e32 v66, v66
	v_add_f32_e32 v65, 1.0, v65
	v_add_f32_e32 v67, 1.0, v66
	v_rcp_f32_e32 v66, v65
	v_rcp_f32_e32 v67, v67
	v_mul_f32_e32 v65, 0xbfb8aa3b, v62
	v_exp_f32_e32 v65, v65
	v_pk_mul_f32 v[60:61], v[60:61], v[66:67]
	v_mul_f32_e32 v66, 0xbfb8aa3b, v63
	v_exp_f32_e32 v66, v66
	v_pk_mul_f32 v[52:53], v[60:61], v[52:53]
	v_add_f32_e32 v60, 1.0, v65
	v_mul_f32_e32 v65, 0xbfb8aa3b, v56
	v_add_f32_e32 v61, 1.0, v66
	v_rcp_f32_e32 v60, v60
	v_rcp_f32_e32 v61, v61
	v_exp_f32_e32 v65, v65
	v_mul_f32_e32 v66, 0xbfb8aa3b, v57
	v_exp_f32_e32 v66, v66
	v_pk_mul_f32 v[60:61], v[62:63], v[60:61]
	v_add_f32_e32 v62, 1.0, v65
	v_mul_f32_e32 v65, 0xbfb8aa3b, v58
	v_add_f32_e32 v63, 1.0, v66
	v_exp_f32_e32 v65, v65
	v_mul_f32_e32 v66, 0xbfb8aa3b, v59
	v_exp_f32_e32 v67, v66
	v_rcp_f32_e32 v62, v62
	v_add_f32_e32 v65, 1.0, v65
	v_rcp_f32_e32 v63, v63
	v_rcp_f32_e32 v66, v65
	v_add_f32_e32 v65, 1.0, v67
	v_rcp_f32_e32 v67, v65
	v_pk_mul_f32 v[56:57], v[56:57], v[62:63]
	v_pk_mul_f32 v[54:55], v[60:61], v[54:55]
	v_pk_mul_f32 v[48:49], v[56:57], v[48:49]
	v_pk_mul_f32 v[56:57], v[58:59], v[66:67]
	s_nop 0
	v_pk_mul_f32 v[50:51], v[56:57], v[50:51]
	s_nop 0
	v_cvt_pk_bf16_f32 v51, v50, v51
	v_cvt_pk_bf16_f32 v50, v48, v49
	v_cvt_pk_bf16_f32 v48, v52, v53
	v_mov_b64_e32 v[52:53], s[8:9]
	v_mad_i64_i32 v[52:53], s[26:27], v64, s58, v[52:53]
	v_cvt_pk_bf16_f32 v49, v54, v55
	v_lshl_add_u64 v[52:53], v[144:145], 1, v[52:53]
	global_store_dwordx4 v[52:53], v[48:51], off sc1
; __device__ __forceinline__ unsigned pk2(float lo, float hi) { f32x2 v = {lo, hi}; bf16x2_t b = __builtin_convertvector(v, bf16x2_t); return __builtin_bit_cast(unsigned, b); }
; __device__ __forceinline__ float sigmoidf_(float x) { return frcp(1.f + fexp2(-1.4426950408889634f * x)); }
;     __device__ __forceinline__ void operator()(const f32x4 (&acc)[2][2][4][2], const Unit& u, int wr, int wc, int fr, int fq) const {
;         const int col0 = u.pn * 128 + wc * 32 + 8 * fq;
; #pragma unroll
;         for (int ai = 0; ai < 2; ++ai)
; #pragma unroll
;             for (int m = 0; m < 4; ++m) {
;                 const int row = u.pm * 256 + ai * 128 + wr * 64 + m * 16 + fr;
;                 float v[8];
; #pragma unroll
;                 for (int n = 0; n < 2; ++n)
; #pragma unroll
;                     for (int i = 0; i < 4; ++i) { const float g = acc[ai][0][m][n][i], up = acc[ai][1][m][n][i]; v[n * 4 + i] = g * sigmoidf_(g) * up; }
;                 u32x4 w; w.x = pk2(v[0], v[1]); w.y = pk2(v[2], v[3]); w.z = pk2(v[4], v[5]); w.w = pk2(v[6], v[7]);
;                 if (row < MR) *(u32x4*)(O + (size_t)row * DFF + col0) = w;
;                 asm volatile("" ::: "memory");
;             }
;     }
.LBB0_162:
	s_or_b64 exec, exec, s[22:23]
	s_nop 0
	v_add_u32_e32 v48, 0x90, v156
	v_cmp_gt_i32_e32 vcc, s57, v48
	s_and_saveexec_b64 s[22:23], vcc
	s_cbranch_execz .LBB0_164
	v_mul_f32_e32 v49, 0xbfb8aa3b, v44
	v_mul_f32_e32 v50, 0xbfb8aa3b, v45
	v_exp_f32_e32 v49, v49
	v_exp_f32_e32 v50, v50
	v_add_f32_e32 v49, 1.0, v49
	v_add_f32_e32 v51, 1.0, v50
	v_rcp_f32_e32 v50, v49
	v_rcp_f32_e32 v51, v51
	v_mul_f32_e32 v49, 0xbfb8aa3b, v46
	v_exp_f32_e32 v49, v49
	v_pk_mul_f32 v[44:45], v[44:45], v[50:51]
	v_mul_f32_e32 v50, 0xbfb8aa3b, v47
	v_exp_f32_e32 v50, v50
	v_pk_mul_f32 v[36:37], v[44:45], v[36:37]
	v_add_f32_e32 v44, 1.0, v49
	v_mul_f32_e32 v49, 0xbfb8aa3b, v40
	v_add_f32_e32 v45, 1.0, v50
	v_rcp_f32_e32 v44, v44
	v_rcp_f32_e32 v45, v45
	v_exp_f32_e32 v49, v49
	v_mul_f32_e32 v50, 0xbfb8aa3b, v41
	v_exp_f32_e32 v50, v50
	v_pk_mul_f32 v[44:45], v[46:47], v[44:45]
	v_add_f32_e32 v46, 1.0, v49
	v_mul_f32_e32 v49, 0xbfb8aa3b, v42
	v_add_f32_e32 v47, 1.0, v50
	v_exp_f32_e32 v49, v49
	v_mul_f32_e32 v50, 0xbfb8aa3b, v43
	v_exp_f32_e32 v51, v50
	v_rcp_f32_e32 v46, v46
	v_add_f32_e32 v49, 1.0, v49
	v_rcp_f32_e32 v47, v47
	v_rcp_f32_e32 v50, v49
	v_add_f32_e32 v49, 1.0, v51
	v_rcp_f32_e32 v51, v49
	v_pk_mul_f32 v[40:41], v[40:41], v[46:47]
	v_pk_mul_f32 v[38:39], v[44:45], v[38:39]
	v_pk_mul_f32 v[32:33], v[40:41], v[32:33]
	v_pk_mul_f32 v[40:41], v[42:43], v[50:51]
	s_nop 0
	v_pk_mul_f32 v[34:35], v[40:41], v[34:35]
	s_nop 0
	v_cvt_pk_bf16_f32 v35, v34, v35
	v_cvt_pk_bf16_f32 v34, v32, v33
	v_cvt_pk_bf16_f32 v32, v36, v37
	v_mov_b64_e32 v[36:37], s[8:9]
	v_mad_i64_i32 v[36:37], s[26:27], v48, s58, v[36:37]
	v_cvt_pk_bf16_f32 v33, v38, v39
	v_lshl_add_u64 v[36:37], v[144:145], 1, v[36:37]
	global_store_dwordx4 v[36:37], v[32:35], off sc1
.LBB0_164:
	s_or_b64 exec, exec, s[22:23]
	s_nop 0
	v_add_u32_e32 v32, 0xa0, v156
	v_cmp_gt_i32_e32 vcc, s57, v32
	s_and_saveexec_b64 s[22:23], vcc
	s_cbranch_execz .LBB0_166
	v_mul_f32_e32 v33, 0xbfb8aa3b, v28
	v_mul_f32_e32 v34, 0xbfb8aa3b, v29
	v_exp_f32_e32 v33, v33
	v_exp_f32_e32 v34, v34
	v_add_f32_e32 v33, 1.0, v33
	v_add_f32_e32 v35, 1.0, v34
	v_rcp_f32_e32 v34, v33
	v_rcp_f32_e32 v35, v35
	v_mul_f32_e32 v33, 0xbfb8aa3b, v30
	v_exp_f32_e32 v33, v33
	v_pk_mul_f32 v[28:29], v[28:29], v[34:35]
	v_mul_f32_e32 v34, 0xbfb8aa3b, v31
	v_exp_f32_e32 v34, v34
	v_pk_mul_f32 v[20:21], v[28:29], v[20:21]
	v_add_f32_e32 v28, 1.0, v33
	v_mul_f32_e32 v33, 0xbfb8aa3b, v24
	v_add_f32_e32 v29, 1.0, v34
	v_rcp_f32_e32 v28, v28
	v_rcp_f32_e32 v29, v29
	v_exp_f32_e32 v33, v33
	v_mul_f32_e32 v34, 0xbfb8aa3b, v25
	v_exp_f32_e32 v34, v34
	v_pk_mul_f32 v[28:29], v[30:31], v[28:29]
	v_add_f32_e32 v30, 1.0, v33
	v_mul_f32_e32 v33, 0xbfb8aa3b, v26
	v_add_f32_e32 v31, 1.0, v34
	v_exp_f32_e32 v33, v33
	v_mul_f32_e32 v34, 0xbfb8aa3b, v27
	v_exp_f32_e32 v35, v34
	v_rcp_f32_e32 v30, v30
	v_add_f32_e32 v33, 1.0, v33
	v_rcp_f32_e32 v31, v31
	v_rcp_f32_e32 v34, v33
	v_add_f32_e32 v33, 1.0, v35
	v_rcp_f32_e32 v35, v33
	v_pk_mul_f32 v[24:25], v[24:25], v[30:31]
	v_pk_mul_f32 v[22:23], v[28:29], v[22:23]
	v_pk_mul_f32 v[16:17], v[24:25], v[16:17]
	v_pk_mul_f32 v[24:25], v[26:27], v[34:35]
	s_nop 0
	v_pk_mul_f32 v[18:19], v[24:25], v[18:19]
	s_nop 0
	v_cvt_pk_bf16_f32 v19, v18, v19
	v_cvt_pk_bf16_f32 v18, v16, v17
	v_cvt_pk_bf16_f32 v16, v20, v21
	v_mov_b64_e32 v[20:21], s[8:9]
	v_mad_i64_i32 v[20:21], s[26:27], v32, s58, v[20:21]
	v_cvt_pk_bf16_f32 v17, v22, v23
	v_lshl_add_u64 v[20:21], v[144:145], 1, v[20:21]
	global_store_dwordx4 v[20:21], v[16:19], off sc1
.LBB0_166:
	s_or_b64 exec, exec, s[22:23]
	s_nop 0
	v_add_u32_e32 v16, 0xb0, v156
	v_cmp_gt_i32_e32 vcc, s57, v16
	s_and_saveexec_b64 s[22:23], vcc
	s_cbranch_execz .LBB0_168
	v_mul_f32_e32 v17, 0xbfb8aa3b, v12
	v_mul_f32_e32 v18, 0xbfb8aa3b, v13
	v_exp_f32_e32 v17, v17
	v_exp_f32_e32 v18, v18
	v_add_f32_e32 v17, 1.0, v17
	v_add_f32_e32 v19, 1.0, v18
	v_rcp_f32_e32 v18, v17
	v_rcp_f32_e32 v19, v19
	v_mul_f32_e32 v17, 0xbfb8aa3b, v14
	v_exp_f32_e32 v17, v17
	v_pk_mul_f32 v[12:13], v[12:13], v[18:19]
	v_mul_f32_e32 v18, 0xbfb8aa3b, v15
	v_exp_f32_e32 v18, v18
	v_pk_mul_f32 v[4:5], v[12:13], v[4:5]
	v_add_f32_e32 v12, 1.0, v17
	v_mul_f32_e32 v17, 0xbfb8aa3b, v8
	v_add_f32_e32 v13, 1.0, v18
	v_rcp_f32_e32 v12, v12
	v_rcp_f32_e32 v13, v13
	v_exp_f32_e32 v17, v17
	v_mul_f32_e32 v18, 0xbfb8aa3b, v9
	v_exp_f32_e32 v18, v18
	v_pk_mul_f32 v[12:13], v[14:15], v[12:13]
	v_add_f32_e32 v14, 1.0, v17
	v_mul_f32_e32 v17, 0xbfb8aa3b, v10
	v_add_f32_e32 v15, 1.0, v18
	v_exp_f32_e32 v17, v17
	v_mul_f32_e32 v18, 0xbfb8aa3b, v11
	v_exp_f32_e32 v19, v18
	v_rcp_f32_e32 v14, v14
	v_add_f32_e32 v17, 1.0, v17
	v_rcp_f32_e32 v15, v15
	v_rcp_f32_e32 v18, v17
	v_add_f32_e32 v17, 1.0, v19
	v_rcp_f32_e32 v19, v17
	v_pk_mul_f32 v[8:9], v[8:9], v[14:15]
	v_pk_mul_f32 v[6:7], v[12:13], v[6:7]
	v_pk_mul_f32 v[0:1], v[8:9], v[0:1]
	v_pk_mul_f32 v[8:9], v[10:11], v[18:19]
	s_nop 0
	v_pk_mul_f32 v[2:3], v[8:9], v[2:3]
	s_nop 0
	v_cvt_pk_bf16_f32 v3, v2, v3
	v_cvt_pk_bf16_f32 v2, v0, v1
	v_cvt_pk_bf16_f32 v0, v4, v5
	v_mov_b64_e32 v[4:5], s[8:9]
	v_mad_i64_i32 v[4:5], s[26:27], v16, s58, v[4:5]
	v_cvt_pk_bf16_f32 v1, v6, v7
	v_lshl_add_u64 v[4:5], v[144:145], 1, v[4:5]
	global_store_dwordx4 v[4:5], v[0:3], off sc1

; #define LAS __attribute__((address_space(3)))
; __device__ __forceinline__ void transpose_item(const float* W, int K, int N, bf16_t* WT, int k0, int n0, int drow0, LAS float* scr, int lane) {
; #pragma unroll 8
;     for (int i = 0; i < 32; ++i) { const int kk = 2 * i + (lane >> 5); scr[kk * 33 + (lane & 31)] = W[(size_t)(k0 + kk) * N + n0 + (lane & 31)]; }
.LBB0_184:
	s_lshl_b32 s23, s20, 1
	s_lshl_b32 s24, s21, 1
	v_or_b32_e32 v2, s23, v1
	v_or_b32_e32 v17, s24, v0
	s_add_i32 s25, s23, 4
	s_add_i32 s26, s24, 4
	s_add_i32 s27, s23, 8
	s_add_i32 s33, s24, 8
	s_add_i32 s34, s23, 12
	s_add_i32 s35, s24, 12
	s_add_i32 s40, s23, 16
	s_add_i32 s41, s24, 16
	s_add_i32 s42, s23, 20
	s_add_i32 s43, s24, 20
	s_add_i32 s44, s23, 24
	s_add_i32 s45, s24, 24
	s_add_i32 s23, s23, 28
	s_add_i32 s24, s24, 28
	v_add_u32_e32 v26, s8, v17
	v_or_b32_e32 v56, s25, v1
	v_or_b32_e32 v57, s26, v0
	v_or_b32_e32 v58, s27, v1
	v_or_b32_e32 v59, s33, v0
	v_or_b32_e32 v60, s34, v1
	v_or_b32_e32 v61, s35, v0
	v_or_b32_e32 v62, s40, v1
	v_or_b32_e32 v63, s41, v0
	v_or_b32_e32 v64, s42, v1
	v_or_b32_e32 v65, s43, v0
	v_or_b32_e32 v66, s44, v1
	v_or_b32_e32 v67, s45, v0
	v_or_b32_e32 v68, s23, v1
	v_or_b32_e32 v69, s24, v0
	v_add_u32_e32 v24, s9, v2
	v_ashrrev_i32_e32 v27, 31, v26
	v_add_u32_e32 v28, s9, v56
	v_add_u32_e32 v30, s8, v57
	v_add_u32_e32 v32, s9, v58
	v_add_u32_e32 v34, s8, v59
	v_add_u32_e32 v36, s9, v60
	v_add_u32_e32 v38, s8, v61
	v_add_u32_e32 v40, s9, v62
	v_add_u32_e32 v42, s8, v63
	v_add_u32_e32 v44, s9, v64
	v_add_u32_e32 v46, s8, v65
	v_add_u32_e32 v48, s9, v66
	v_add_u32_e32 v50, s8, v67
	v_add_u32_e32 v52, s9, v68
	v_add_u32_e32 v54, s8, v69
	v_ashrrev_i32_e32 v25, 31, v24
	v_lshlrev_b64 v[26:27], 12, v[26:27]
	v_ashrrev_i32_e32 v31, 31, v30
	v_ashrrev_i32_e32 v29, 31, v28
	v_ashrrev_i32_e32 v35, 31, v34
	v_ashrrev_i32_e32 v33, 31, v32
	v_ashrrev_i32_e32 v39, 31, v38
	v_ashrrev_i32_e32 v37, 31, v36
	v_ashrrev_i32_e32 v43, 31, v42
	v_ashrrev_i32_e32 v41, 31, v40
	v_ashrrev_i32_e32 v47, 31, v46
	v_ashrrev_i32_e32 v45, 31, v44
	v_ashrrev_i32_e32 v51, 31, v50
	v_ashrrev_i32_e32 v49, 31, v48
	v_ashrrev_i32_e32 v55, 31, v54
	v_ashrrev_i32_e32 v53, 31, v52
	v_lshlrev_b64 v[24:25], 12, v[24:25]
	v_lshl_add_u64 v[26:27], v[18:19], 0, v[26:27]
	v_lshlrev_b64 v[28:29], 12, v[28:29]
	v_lshlrev_b64 v[30:31], 12, v[30:31]
	v_lshlrev_b64 v[32:33], 12, v[32:33]
	v_lshlrev_b64 v[34:35], 12, v[34:35]
	v_lshlrev_b64 v[36:37], 12, v[36:37]
	v_lshlrev_b64 v[38:39], 12, v[38:39]
	v_lshlrev_b64 v[40:41], 12, v[40:41]
	v_lshlrev_b64 v[42:43], 12, v[42:43]
	v_lshlrev_b64 v[44:45], 12, v[44:45]
	v_lshlrev_b64 v[46:47], 12, v[46:47]
	v_lshlrev_b64 v[48:49], 12, v[48:49]
	v_lshlrev_b64 v[50:51], 12, v[50:51]
	v_lshlrev_b64 v[52:53], 12, v[52:53]
	v_lshlrev_b64 v[54:55], 12, v[54:55]
	v_lshl_add_u64 v[24:25], v[18:19], 0, v[24:25]
	v_lshl_add_u64 v[30:31], v[18:19], 0, v[30:31]
	v_lshl_add_u64 v[28:29], v[18:19], 0, v[28:29]
	v_lshl_add_u64 v[34:35], v[18:19], 0, v[34:35]
	v_lshl_add_u64 v[32:33], v[18:19], 0, v[32:33]
	v_lshl_add_u64 v[38:39], v[18:19], 0, v[38:39]
	v_lshl_add_u64 v[36:37], v[18:19], 0, v[36:37]
	v_lshl_add_u64 v[42:43], v[18:19], 0, v[42:43]
	v_lshl_add_u64 v[40:41], v[18:19], 0, v[40:41]
	v_lshl_add_u64 v[46:47], v[18:19], 0, v[46:47]
	v_lshl_add_u64 v[44:45], v[18:19], 0, v[44:45]
	v_lshl_add_u64 v[50:51], v[18:19], 0, v[50:51]
	v_lshl_add_u64 v[48:49], v[18:19], 0, v[48:49]
	v_lshl_add_u64 v[54:55], v[18:19], 0, v[54:55]
	v_lshl_add_u64 v[52:53], v[18:19], 0, v[52:53]
	global_load_dword v70, v[26:27], off
	global_load_dword v71, v[24:25], off
	global_load_dword v72, v[30:31], off
	global_load_dword v73, v[28:29], off
	global_load_dword v74, v[34:35], off
	global_load_dword v75, v[32:33], off
	global_load_dword v76, v[38:39], off
	global_load_dword v77, v[36:37], off
	global_load_dword v78, v[42:43], off
	global_load_dword v79, v[40:41], off
	global_load_dword v80, v[46:47], off
	global_load_dword v81, v[44:45], off
	global_load_dword v82, v[50:51], off
	global_load_dword v83, v[48:49], off
	global_load_dword v84, v[54:55], off
	global_load_dword v85, v[52:53], off
	s_add_i32 s21, s21, 16
	s_add_i32 s20, s20, 16
	s_add_i32 s22, s22, -16
	v_mad_u64_u32 v[24:25], s[24:25], v17, s12, v[4:5]
	s_cmp_lg_u32 s22, 0
	v_mad_u64_u32 v[26:27], s[24:25], v2, s12, v[4:5]
	v_mad_u64_u32 v[28:29], s[24:25], v57, s12, v[4:5]
	v_mad_u64_u32 v[30:31], s[24:25], v56, s12, v[4:5]
	v_mad_u64_u32 v[32:33], s[24:25], v59, s12, v[4:5]
	v_mad_u64_u32 v[34:35], s[24:25], v58, s12, v[4:5]
	v_mad_u64_u32 v[36:37], s[24:25], v61, s12, v[4:5]
	v_mad_u64_u32 v[38:39], s[24:25], v60, s12, v[4:5]
	v_mad_u64_u32 v[40:41], s[24:25], v63, s12, v[4:5]
	v_mad_u64_u32 v[42:43], s[24:25], v62, s12, v[4:5]
	v_mad_u64_u32 v[44:45], s[24:25], v65, s12, v[4:5]
	v_mad_u64_u32 v[46:47], s[24:25], v64, s12, v[4:5]
	v_mad_u64_u32 v[48:49], s[24:25], v67, s12, v[4:5]
	v_mad_u64_u32 v[50:51], s[24:25], v66, s12, v[4:5]
	v_mad_u64_u32 v[52:53], s[24:25], v69, s12, v[4:5]
	v_mad_u64_u32 v[54:55], s[24:25], v68, s12, v[4:5]
	s_waitcnt vmcnt(15)
	ds_write_b32 v24, v70
	s_waitcnt vmcnt(14)
	ds_write_b32 v26, v71
	s_waitcnt vmcnt(13)
	ds_write_b32 v28, v72
	s_waitcnt vmcnt(12)
	ds_write_b32 v30, v73
	s_waitcnt vmcnt(11)
	ds_write_b32 v32, v74
	s_waitcnt vmcnt(10)
	ds_write_b32 v34, v75
	s_waitcnt vmcnt(9)
	ds_write_b32 v36, v76
	s_waitcnt vmcnt(8)
	ds_write_b32 v38, v77
	s_waitcnt vmcnt(7)
	ds_write_b32 v40, v78
	s_waitcnt vmcnt(6)
	ds_write_b32 v42, v79
	s_waitcnt vmcnt(5)
	ds_write_b32 v44, v80
	s_waitcnt vmcnt(4)
	ds_write_b32 v46, v81
	s_waitcnt vmcnt(3)
	ds_write_b32 v48, v82
	s_waitcnt vmcnt(2)
	ds_write_b32 v50, v83
	s_waitcnt vmcnt(1)
	ds_write_b32 v52, v84
	s_waitcnt vmcnt(0)
	ds_write_b32 v54, v85
	s_cbranch_scc1 .LBB0_184
; #define LAS __attribute__((address_space(3)))
; __device__ __forceinline__ unsigned pk2(float lo, float hi) { f32x2 v = {lo, hi}; bf16x2_t b = __builtin_convertvector(v, bf16x2_t); return __builtin_bit_cast(unsigned, b); }
; __device__ __forceinline__ void transpose_item(const float* W, int K, int N, bf16_t* WT, int k0, int n0, int drow0, LAS float* scr, int lane) {
;     ...
;     asm volatile("s_waitcnt lgkmcnt(0)" ::: "memory");
;     const int c = lane & 7;
; #pragma unroll
;     for (int j = 0; j < 4; ++j) { const int n = (lane >> 3) + 8 * j; const LAS float* s = scr + (8 * c) * 33 + n;
;         u32x4 o; o.x = pk2(s[0 * 33], s[1 * 33]); o.y = pk2(s[2 * 33], s[3 * 33]); o.z = pk2(s[4 * 33], s[5 * 33]); o.w = pk2(s[6 * 33], s[7 * 33]);
;         *(u32x4*)(WT + (size_t)(drow0 + n) * K + k0 + 8 * c) = o; }
;     asm volatile("s_waitcnt lgkmcnt(0)" ::: "memory");
	s_waitcnt lgkmcnt(0)
	ds_read2_b32 v[18:19], v20 offset0:33 offset1:41
	ds_read2_b32 v[28:29], v20 offset1:8
	ds_read2_b32 v[30:31], v20 offset0:66 offset1:74
	ds_read2_b32 v[32:33], v20 offset0:99 offset1:107
	ds_read2_b32 v[34:35], v20 offset0:132 offset1:140
	ds_read2_b32 v[36:37], v20 offset0:165 offset1:173
	ds_read2_b32 v[38:39], v20 offset0:198 offset1:206
	ds_read2_b32 v[40:41], v20 offset0:231 offset1:239
	s_mov_b32 s9, s3
	v_or_b32_e32 v2, s2, v5
	v_lshl_add_u64 v[42:43], s[8:9], 1, v[6:7]
	v_lshlrev_b32_e32 v2, 11, v2
	s_waitcnt lgkmcnt(6)
	v_cvt_pk_bf16_f32 v24, v28, v18
	s_waitcnt lgkmcnt(4)
	v_cvt_pk_bf16_f32 v25, v30, v32
	s_waitcnt lgkmcnt(2)
	v_cvt_pk_bf16_f32 v26, v34, v36
	s_waitcnt lgkmcnt(0)
	v_cvt_pk_bf16_f32 v27, v38, v40
	v_lshl_add_u64 v[44:45], v[42:43], 0, v[2:3]
	global_store_dwordx4 v[44:45], v[24:27], off sc1
	v_or_b32_e32 v2, s2, v21
	v_lshlrev_b32_e32 v2, 11, v2
	v_cvt_pk_bf16_f32 v24, v29, v19
	v_cvt_pk_bf16_f32 v25, v31, v33
	v_cvt_pk_bf16_f32 v26, v35, v37
	v_cvt_pk_bf16_f32 v27, v39, v41
	ds_read2_b32 v[28:29], v20 offset0:49 offset1:57
	ds_read2_b32 v[30:31], v20 offset0:16 offset1:24
	ds_read2_b32 v[32:33], v20 offset0:82 offset1:90
	ds_read2_b32 v[34:35], v20 offset0:115 offset1:123
	ds_read2_b32 v[36:37], v20 offset0:148 offset1:156
	ds_read2_b32 v[38:39], v20 offset0:181 offset1:189
	ds_read2_b32 v[40:41], v20 offset0:214 offset1:222
	ds_read2_b32 v[44:45], v20 offset0:247 offset1:255
	v_lshl_add_u64 v[18:19], v[42:43], 0, v[2:3]
	v_or_b32_e32 v2, s2, v22
	v_lshlrev_b32_e32 v2, 11, v2
	global_store_dwordx4 v[18:19], v[24:27], off sc1
	v_lshl_add_u64 v[18:19], v[42:43], 0, v[2:3]
	v_or_b32_e32 v2, s2, v23
	s_waitcnt lgkmcnt(6)
	v_cvt_pk_bf16_f32 v24, v30, v28
	s_waitcnt lgkmcnt(4)
	v_cvt_pk_bf16_f32 v25, v32, v34
	s_waitcnt lgkmcnt(2)
	v_cvt_pk_bf16_f32 v26, v36, v38
	s_waitcnt lgkmcnt(0)
	v_cvt_pk_bf16_f32 v27, v40, v44
	v_lshlrev_b32_e32 v2, 11, v2
	global_store_dwordx4 v[18:19], v[24:27], off sc1
	v_lshl_add_u64 v[18:19], v[42:43], 0, v[2:3]
	s_mov_b64 s[8:9], 0
	v_cvt_pk_bf16_f32 v24, v31, v29
	v_cvt_pk_bf16_f32 v25, v33, v35
	v_cvt_pk_bf16_f32 v26, v37, v39
	v_cvt_pk_bf16_f32 v27, v41, v45
	global_store_dwordx4 v[18:19], v[24:27], off sc1
	s_waitcnt lgkmcnt(0)

; #define LAS __attribute__((address_space(3)))
; __device__ __forceinline__ void transpose_item(const float* W, int K, int N, bf16_t* WT, int k0, int n0, int drow0, LAS float* scr, int lane) {
; #pragma unroll 8
;     for (int i = 0; i < 32; ++i) { const int kk = 2 * i + (lane >> 5); scr[kk * 33 + (lane & 31)] = W[(size_t)(k0 + kk) * N + n0 + (lane & 31)]; }
.LBB0_188:
	s_lshl_b32 s22, s19, 1
	s_lshl_b32 s23, s20, 1
	v_or_b32_e32 v2, s22, v1
	v_or_b32_e32 v17, s23, v0
	s_add_i32 s24, s22, 4
	s_add_i32 s25, s23, 4
	s_add_i32 s26, s22, 8
	s_add_i32 s27, s23, 8
	s_add_i32 s33, s22, 12
	s_add_i32 s34, s23, 12
	s_add_i32 s35, s22, 16
	s_add_i32 s40, s23, 16
	s_add_i32 s41, s22, 20
	s_add_i32 s42, s23, 20
	s_add_i32 s43, s22, 24
	s_add_i32 s44, s23, 24
	s_add_i32 s22, s22, 28
	s_add_i32 s23, s23, 28
	v_add_u32_e32 v26, s8, v17
	v_or_b32_e32 v56, s24, v1
	v_or_b32_e32 v57, s25, v0
	v_or_b32_e32 v58, s26, v1
	v_or_b32_e32 v59, s27, v0
	v_or_b32_e32 v60, s33, v1
	v_or_b32_e32 v61, s34, v0
	v_or_b32_e32 v62, s35, v1
	v_or_b32_e32 v63, s40, v0
	v_or_b32_e32 v64, s41, v1
	v_or_b32_e32 v65, s42, v0
	v_or_b32_e32 v66, s43, v1
	v_or_b32_e32 v67, s44, v0
	v_or_b32_e32 v68, s22, v1
	v_or_b32_e32 v69, s23, v0
	v_add_u32_e32 v24, s9, v2
	v_ashrrev_i32_e32 v27, 31, v26
	v_add_u32_e32 v28, s9, v56
	v_add_u32_e32 v30, s8, v57
	v_add_u32_e32 v32, s9, v58
	v_add_u32_e32 v34, s8, v59
	v_add_u32_e32 v36, s9, v60
	v_add_u32_e32 v38, s8, v61
	v_add_u32_e32 v40, s9, v62
	v_add_u32_e32 v42, s8, v63
	v_add_u32_e32 v44, s9, v64
	v_add_u32_e32 v46, s8, v65
	v_add_u32_e32 v48, s9, v66
	v_add_u32_e32 v50, s8, v67
	v_add_u32_e32 v52, s9, v68
	v_add_u32_e32 v54, s8, v69
	v_ashrrev_i32_e32 v25, 31, v24
	v_lshlrev_b64 v[26:27], 12, v[26:27]
	v_ashrrev_i32_e32 v31, 31, v30
	v_ashrrev_i32_e32 v29, 31, v28
	v_ashrrev_i32_e32 v35, 31, v34
	v_ashrrev_i32_e32 v33, 31, v32
	v_ashrrev_i32_e32 v39, 31, v38
	v_ashrrev_i32_e32 v37, 31, v36
	v_ashrrev_i32_e32 v43, 31, v42
	v_ashrrev_i32_e32 v41, 31, v40
	v_ashrrev_i32_e32 v47, 31, v46
	v_ashrrev_i32_e32 v45, 31, v44
	v_ashrrev_i32_e32 v51, 31, v50
	v_ashrrev_i32_e32 v49, 31, v48
	v_ashrrev_i32_e32 v55, 31, v54
	v_ashrrev_i32_e32 v53, 31, v52
	v_lshlrev_b64 v[24:25], 12, v[24:25]
	v_lshl_add_u64 v[26:27], v[18:19], 0, v[26:27]
	v_lshlrev_b64 v[28:29], 12, v[28:29]
	v_lshlrev_b64 v[30:31], 12, v[30:31]
	v_lshlrev_b64 v[32:33], 12, v[32:33]
	v_lshlrev_b64 v[34:35], 12, v[34:35]
	v_lshlrev_b64 v[36:37], 12, v[36:37]
	v_lshlrev_b64 v[38:39], 12, v[38:39]
	v_lshlrev_b64 v[40:41], 12, v[40:41]
	v_lshlrev_b64 v[42:43], 12, v[42:43]
	v_lshlrev_b64 v[44:45], 12, v[44:45]
	v_lshlrev_b64 v[46:47], 12, v[46:47]
	v_lshlrev_b64 v[48:49], 12, v[48:49]
	v_lshlrev_b64 v[50:51], 12, v[50:51]
	v_lshlrev_b64 v[52:53], 12, v[52:53]
	v_lshlrev_b64 v[54:55], 12, v[54:55]
	v_lshl_add_u64 v[24:25], v[18:19], 0, v[24:25]
	v_lshl_add_u64 v[30:31], v[18:19], 0, v[30:31]
	v_lshl_add_u64 v[28:29], v[18:19], 0, v[28:29]
	v_lshl_add_u64 v[34:35], v[18:19], 0, v[34:35]
	v_lshl_add_u64 v[32:33], v[18:19], 0, v[32:33]
	v_lshl_add_u64 v[38:39], v[18:19], 0, v[38:39]
	v_lshl_add_u64 v[36:37], v[18:19], 0, v[36:37]
	v_lshl_add_u64 v[42:43], v[18:19], 0, v[42:43]
	v_lshl_add_u64 v[40:41], v[18:19], 0, v[40:41]
	v_lshl_add_u64 v[46:47], v[18:19], 0, v[46:47]
	v_lshl_add_u64 v[44:45], v[18:19], 0, v[44:45]
	v_lshl_add_u64 v[50:51], v[18:19], 0, v[50:51]
	v_lshl_add_u64 v[48:49], v[18:19], 0, v[48:49]
	v_lshl_add_u64 v[54:55], v[18:19], 0, v[54:55]
	v_lshl_add_u64 v[52:53], v[18:19], 0, v[52:53]
	global_load_dword v70, v[26:27], off
	global_load_dword v71, v[24:25], off
	global_load_dword v72, v[30:31], off
	global_load_dword v73, v[28:29], off
	global_load_dword v74, v[34:35], off
	global_load_dword v75, v[32:33], off
	global_load_dword v76, v[38:39], off
	global_load_dword v77, v[36:37], off
	global_load_dword v78, v[42:43], off
	global_load_dword v79, v[40:41], off
	global_load_dword v80, v[46:47], off
	global_load_dword v81, v[44:45], off
	global_load_dword v82, v[50:51], off
	global_load_dword v83, v[48:49], off
	global_load_dword v84, v[54:55], off
	global_load_dword v85, v[52:53], off
	s_add_i32 s20, s20, 16
	s_add_i32 s19, s19, 16
	s_add_i32 s21, s21, -16
	v_mad_u64_u32 v[24:25], s[22:23], v17, s12, v[4:5]
	s_cmp_lg_u32 s21, 0
	v_mad_u64_u32 v[26:27], s[22:23], v2, s12, v[4:5]
	v_mad_u64_u32 v[28:29], s[22:23], v57, s12, v[4:5]
	v_mad_u64_u32 v[30:31], s[22:23], v56, s12, v[4:5]
	v_mad_u64_u32 v[32:33], s[22:23], v59, s12, v[4:5]
	v_mad_u64_u32 v[34:35], s[22:23], v58, s12, v[4:5]
	v_mad_u64_u32 v[36:37], s[22:23], v61, s12, v[4:5]
	v_mad_u64_u32 v[38:39], s[22:23], v60, s12, v[4:5]
	v_mad_u64_u32 v[40:41], s[22:23], v63, s12, v[4:5]
	v_mad_u64_u32 v[42:43], s[22:23], v62, s12, v[4:5]
	v_mad_u64_u32 v[44:45], s[22:23], v65, s12, v[4:5]
	v_mad_u64_u32 v[46:47], s[22:23], v64, s12, v[4:5]
	v_mad_u64_u32 v[48:49], s[22:23], v67, s12, v[4:5]
	v_mad_u64_u32 v[50:51], s[22:23], v66, s12, v[4:5]
	v_mad_u64_u32 v[52:53], s[22:23], v69, s12, v[4:5]
	v_mad_u64_u32 v[54:55], s[22:23], v68, s12, v[4:5]
	s_waitcnt vmcnt(15)
	ds_write_b32 v24, v70
	s_waitcnt vmcnt(14)
	ds_write_b32 v26, v71
	s_waitcnt vmcnt(13)
	ds_write_b32 v28, v72
	s_waitcnt vmcnt(12)
	ds_write_b32 v30, v73
	s_waitcnt vmcnt(11)
	ds_write_b32 v32, v74
	s_waitcnt vmcnt(10)
	ds_write_b32 v34, v75
	s_waitcnt vmcnt(9)
	ds_write_b32 v36, v76
	s_waitcnt vmcnt(8)
	ds_write_b32 v38, v77
	s_waitcnt vmcnt(7)
	ds_write_b32 v40, v78
	s_waitcnt vmcnt(6)
	ds_write_b32 v42, v79
	s_waitcnt vmcnt(5)
	ds_write_b32 v44, v80
	s_waitcnt vmcnt(4)
	ds_write_b32 v46, v81
	s_waitcnt vmcnt(3)
	ds_write_b32 v48, v82
	s_waitcnt vmcnt(2)
	ds_write_b32 v50, v83
	s_waitcnt vmcnt(1)
	ds_write_b32 v52, v84
	s_waitcnt vmcnt(0)
	ds_write_b32 v54, v85
	s_cbranch_scc1 .LBB0_188
; #define LAS __attribute__((address_space(3)))
; __device__ __forceinline__ unsigned pk2(float lo, float hi) { f32x2 v = {lo, hi}; bf16x2_t b = __builtin_convertvector(v, bf16x2_t); return __builtin_bit_cast(unsigned, b); }
; __device__ __forceinline__ void transpose_item(const float* W, int K, int N, bf16_t* WT, int k0, int n0, int drow0, LAS float* scr, int lane) {
;     ...
;     asm volatile("s_waitcnt lgkmcnt(0)" ::: "memory");
;     const int c = lane & 7;
; #pragma unroll
;     for (int j = 0; j < 4; ++j) { const int n = (lane >> 3) + 8 * j; const LAS float* s = scr + (8 * c) * 33 + n;
;         u32x4 o; o.x = pk2(s[0 * 33], s[1 * 33]); o.y = pk2(s[2 * 33], s[3 * 33]); o.z = pk2(s[4 * 33], s[5 * 33]); o.w = pk2(s[6 * 33], s[7 * 33]);
;         *(u32x4*)(WT + (size_t)(drow0 + n) * K + k0 + 8 * c) = o; }
;     asm volatile("s_waitcnt lgkmcnt(0)" ::: "memory");
	s_waitcnt lgkmcnt(0)
	ds_read2_b32 v[18:19], v20 offset0:33 offset1:41
	ds_read2_b32 v[28:29], v20 offset1:8
	ds_read2_b32 v[30:31], v20 offset0:66 offset1:74
	ds_read2_b32 v[32:33], v20 offset0:99 offset1:107
	ds_read2_b32 v[34:35], v20 offset0:132 offset1:140
	ds_read2_b32 v[36:37], v20 offset0:165 offset1:173
	ds_read2_b32 v[38:39], v20 offset0:198 offset1:206
	ds_read2_b32 v[40:41], v20 offset0:231 offset1:239
	s_mov_b32 s9, s3
	v_or_b32_e32 v2, s2, v5
	v_lshl_add_u64 v[42:43], s[8:9], 1, v[8:9]
	v_lshlrev_b32_e32 v2, 10, v2
	s_waitcnt lgkmcnt(6)
	v_cvt_pk_bf16_f32 v24, v28, v18
	s_waitcnt lgkmcnt(4)
	v_cvt_pk_bf16_f32 v25, v30, v32
	s_waitcnt lgkmcnt(2)
	v_cvt_pk_bf16_f32 v26, v34, v36
	s_waitcnt lgkmcnt(0)
	v_cvt_pk_bf16_f32 v27, v38, v40
	v_lshl_add_u64 v[44:45], v[42:43], 0, v[2:3]
	global_store_dwordx4 v[44:45], v[24:27], off sc1
	v_or_b32_e32 v2, s2, v21
	v_lshlrev_b32_e32 v2, 10, v2
	v_cvt_pk_bf16_f32 v24, v29, v19
	v_cvt_pk_bf16_f32 v25, v31, v33
	v_cvt_pk_bf16_f32 v26, v35, v37
	v_cvt_pk_bf16_f32 v27, v39, v41
	ds_read2_b32 v[28:29], v20 offset0:49 offset1:57
	ds_read2_b32 v[30:31], v20 offset0:16 offset1:24
	ds_read2_b32 v[32:33], v20 offset0:82 offset1:90
	ds_read2_b32 v[34:35], v20 offset0:115 offset1:123
	ds_read2_b32 v[36:37], v20 offset0:148 offset1:156
	ds_read2_b32 v[38:39], v20 offset0:181 offset1:189
	ds_read2_b32 v[40:41], v20 offset0:214 offset1:222
	ds_read2_b32 v[44:45], v20 offset0:247 offset1:255
	v_lshl_add_u64 v[18:19], v[42:43], 0, v[2:3]
	v_or_b32_e32 v2, s2, v22
	v_lshlrev_b32_e32 v2, 10, v2
	global_store_dwordx4 v[18:19], v[24:27], off sc1
	v_lshl_add_u64 v[18:19], v[42:43], 0, v[2:3]
	v_or_b32_e32 v2, s2, v23
	s_waitcnt lgkmcnt(6)
	v_cvt_pk_bf16_f32 v24, v30, v28
	s_waitcnt lgkmcnt(4)
	v_cvt_pk_bf16_f32 v25, v32, v34
	s_waitcnt lgkmcnt(2)
	v_cvt_pk_bf16_f32 v26, v36, v38
	s_waitcnt lgkmcnt(0)
	v_cvt_pk_bf16_f32 v27, v40, v44
	v_lshlrev_b32_e32 v2, 10, v2
	global_store_dwordx4 v[18:19], v[24:27], off sc1
	v_lshl_add_u64 v[18:19], v[42:43], 0, v[2:3]
	s_nop 0
	v_cvt_pk_bf16_f32 v24, v31, v29
	v_cvt_pk_bf16_f32 v25, v33, v35
	v_cvt_pk_bf16_f32 v26, v37, v39
	v_cvt_pk_bf16_f32 v27, v41, v45
	global_store_dwordx4 v[18:19], v[24:27], off sc1
	s_waitcnt lgkmcnt(0)

; #define LAS __attribute__((address_space(3)))
; __device__ __forceinline__ void transpose_item(const float* W, int K, int N, bf16_t* WT, int k0, int n0, int drow0, LAS float* scr, int lane) {
; #pragma unroll 8
;     for (int i = 0; i < 32; ++i) { const int kk = 2 * i + (lane >> 5); scr[kk * 33 + (lane & 31)] = W[(size_t)(k0 + kk) * N + n0 + (lane & 31)]; }
.LBB0_193:
	s_lshl_b32 s22, s9, 1
	s_lshl_b32 s23, s20, 1
	v_or_b32_e32 v2, s22, v1
	v_or_b32_e32 v17, s23, v0
	s_add_i32 s24, s22, 4
	s_add_i32 s25, s23, 4
	s_add_i32 s26, s22, 8
	s_add_i32 s27, s23, 8
	s_add_i32 s33, s22, 12
	s_add_i32 s34, s23, 12
	s_add_i32 s35, s22, 16
	s_add_i32 s40, s23, 16
	s_add_i32 s41, s22, 20
	s_add_i32 s42, s23, 20
	s_add_i32 s43, s22, 24
	s_add_i32 s44, s23, 24
	s_add_i32 s22, s22, 28
	s_add_i32 s23, s23, 28
	v_add_u32_e32 v26, s8, v17
	v_or_b32_e32 v56, s24, v1
	v_or_b32_e32 v57, s25, v0
	v_or_b32_e32 v58, s26, v1
	v_or_b32_e32 v59, s27, v0
	v_or_b32_e32 v60, s33, v1
	v_or_b32_e32 v61, s34, v0
	v_or_b32_e32 v62, s35, v1
	v_or_b32_e32 v63, s40, v0
	v_or_b32_e32 v64, s41, v1
	v_or_b32_e32 v65, s42, v0
	v_or_b32_e32 v66, s43, v1
	v_or_b32_e32 v67, s44, v0
	v_or_b32_e32 v68, s22, v1
	v_or_b32_e32 v69, s23, v0
	v_add_u32_e32 v24, s19, v2
	v_ashrrev_i32_e32 v27, 31, v26
	v_add_u32_e32 v28, s19, v56
	v_add_u32_e32 v30, s8, v57
	v_add_u32_e32 v32, s19, v58
	v_add_u32_e32 v34, s8, v59
	v_add_u32_e32 v36, s19, v60
	v_add_u32_e32 v38, s8, v61
	v_add_u32_e32 v40, s19, v62
	v_add_u32_e32 v42, s8, v63
	v_add_u32_e32 v44, s19, v64
	v_add_u32_e32 v46, s8, v65
	v_add_u32_e32 v48, s19, v66
	v_add_u32_e32 v50, s8, v67
	v_add_u32_e32 v52, s19, v68
	v_add_u32_e32 v54, s8, v69
	v_ashrrev_i32_e32 v25, 31, v24
	v_lshlrev_b64 v[26:27], 12, v[26:27]
	v_ashrrev_i32_e32 v31, 31, v30
	v_ashrrev_i32_e32 v29, 31, v28
	v_ashrrev_i32_e32 v35, 31, v34
	v_ashrrev_i32_e32 v33, 31, v32
	v_ashrrev_i32_e32 v39, 31, v38
	v_ashrrev_i32_e32 v37, 31, v36
	v_ashrrev_i32_e32 v43, 31, v42
	v_ashrrev_i32_e32 v41, 31, v40
	v_ashrrev_i32_e32 v47, 31, v46
	v_ashrrev_i32_e32 v45, 31, v44
	v_ashrrev_i32_e32 v51, 31, v50
	v_ashrrev_i32_e32 v49, 31, v48
	v_ashrrev_i32_e32 v55, 31, v54
	v_ashrrev_i32_e32 v53, 31, v52
	v_lshlrev_b64 v[24:25], 12, v[24:25]
	v_lshl_add_u64 v[26:27], v[18:19], 0, v[26:27]
	v_lshlrev_b64 v[28:29], 12, v[28:29]
	v_lshlrev_b64 v[30:31], 12, v[30:31]
	v_lshlrev_b64 v[32:33], 12, v[32:33]
	v_lshlrev_b64 v[34:35], 12, v[34:35]
	v_lshlrev_b64 v[36:37], 12, v[36:37]
	v_lshlrev_b64 v[38:39], 12, v[38:39]
	v_lshlrev_b64 v[40:41], 12, v[40:41]
	v_lshlrev_b64 v[42:43], 12, v[42:43]
	v_lshlrev_b64 v[44:45], 12, v[44:45]
	v_lshlrev_b64 v[46:47], 12, v[46:47]
	v_lshlrev_b64 v[48:49], 12, v[48:49]
	v_lshlrev_b64 v[50:51], 12, v[50:51]
	v_lshlrev_b64 v[52:53], 12, v[52:53]
	v_lshlrev_b64 v[54:55], 12, v[54:55]
	v_lshl_add_u64 v[24:25], v[18:19], 0, v[24:25]
	v_lshl_add_u64 v[30:31], v[18:19], 0, v[30:31]
	v_lshl_add_u64 v[28:29], v[18:19], 0, v[28:29]
	v_lshl_add_u64 v[34:35], v[18:19], 0, v[34:35]
	v_lshl_add_u64 v[32:33], v[18:19], 0, v[32:33]
	v_lshl_add_u64 v[38:39], v[18:19], 0, v[38:39]
	v_lshl_add_u64 v[36:37], v[18:19], 0, v[36:37]
	v_lshl_add_u64 v[42:43], v[18:19], 0, v[42:43]
	v_lshl_add_u64 v[40:41], v[18:19], 0, v[40:41]
	v_lshl_add_u64 v[46:47], v[18:19], 0, v[46:47]
	v_lshl_add_u64 v[44:45], v[18:19], 0, v[44:45]
	v_lshl_add_u64 v[50:51], v[18:19], 0, v[50:51]
	v_lshl_add_u64 v[48:49], v[18:19], 0, v[48:49]
	v_lshl_add_u64 v[54:55], v[18:19], 0, v[54:55]
	v_lshl_add_u64 v[52:53], v[18:19], 0, v[52:53]
	global_load_dword v70, v[26:27], off
	global_load_dword v71, v[24:25], off
	global_load_dword v72, v[30:31], off
	global_load_dword v73, v[28:29], off
	global_load_dword v74, v[34:35], off
	global_load_dword v75, v[32:33], off
	global_load_dword v76, v[38:39], off
	global_load_dword v77, v[36:37], off
	global_load_dword v78, v[42:43], off
	global_load_dword v79, v[40:41], off
	global_load_dword v80, v[46:47], off
	global_load_dword v81, v[44:45], off
	global_load_dword v82, v[50:51], off
	global_load_dword v83, v[48:49], off
	global_load_dword v84, v[54:55], off
	global_load_dword v85, v[52:53], off
	s_add_i32 s20, s20, 16
	s_add_i32 s9, s9, 16
	s_add_i32 s21, s21, -16
	v_mad_u64_u32 v[24:25], s[22:23], v17, s12, v[4:5]
	s_cmp_lg_u32 s21, 0
	v_mad_u64_u32 v[26:27], s[22:23], v2, s12, v[4:5]
	v_mad_u64_u32 v[28:29], s[22:23], v57, s12, v[4:5]
	v_mad_u64_u32 v[30:31], s[22:23], v56, s12, v[4:5]
	v_mad_u64_u32 v[32:33], s[22:23], v59, s12, v[4:5]
	v_mad_u64_u32 v[34:35], s[22:23], v58, s12, v[4:5]
	v_mad_u64_u32 v[36:37], s[22:23], v61, s12, v[4:5]
	v_mad_u64_u32 v[38:39], s[22:23], v60, s12, v[4:5]
	v_mad_u64_u32 v[40:41], s[22:23], v63, s12, v[4:5]
	v_mad_u64_u32 v[42:43], s[22:23], v62, s12, v[4:5]
	v_mad_u64_u32 v[44:45], s[22:23], v65, s12, v[4:5]
	v_mad_u64_u32 v[46:47], s[22:23], v64, s12, v[4:5]
	v_mad_u64_u32 v[48:49], s[22:23], v67, s12, v[4:5]
	v_mad_u64_u32 v[50:51], s[22:23], v66, s12, v[4:5]
	v_mad_u64_u32 v[52:53], s[22:23], v69, s12, v[4:5]
	v_mad_u64_u32 v[54:55], s[22:23], v68, s12, v[4:5]
	s_waitcnt vmcnt(15)
	ds_write_b32 v24, v70
	s_waitcnt vmcnt(14)
	ds_write_b32 v26, v71
	s_waitcnt vmcnt(13)
	ds_write_b32 v28, v72
	s_waitcnt vmcnt(12)
	ds_write_b32 v30, v73
	s_waitcnt vmcnt(11)
	ds_write_b32 v32, v74
	s_waitcnt vmcnt(10)
	ds_write_b32 v34, v75
	s_waitcnt vmcnt(9)
	ds_write_b32 v36, v76
	s_waitcnt vmcnt(8)
	ds_write_b32 v38, v77
	s_waitcnt vmcnt(7)
	ds_write_b32 v40, v78
	s_waitcnt vmcnt(6)
	ds_write_b32 v42, v79
	s_waitcnt vmcnt(5)
	ds_write_b32 v44, v80
	s_waitcnt vmcnt(4)
	ds_write_b32 v46, v81
	s_waitcnt vmcnt(3)
	ds_write_b32 v48, v82
	s_waitcnt vmcnt(2)
	ds_write_b32 v50, v83
	s_waitcnt vmcnt(1)
	ds_write_b32 v52, v84
	s_waitcnt vmcnt(0)
	ds_write_b32 v54, v85
	s_cbranch_scc1 .LBB0_193
; #define LAS __attribute__((address_space(3)))
; __device__ __forceinline__ unsigned pk2(float lo, float hi) { f32x2 v = {lo, hi}; bf16x2_t b = __builtin_convertvector(v, bf16x2_t); return __builtin_bit_cast(unsigned, b); }
; __device__ __forceinline__ void transpose_item(const float* W, int K, int N, bf16_t* WT, int k0, int n0, int drow0, LAS float* scr, int lane) {
;     ...
;     asm volatile("s_waitcnt lgkmcnt(0)" ::: "memory");
;     const int c = lane & 7;
; #pragma unroll
;     for (int j = 0; j < 4; ++j) { const int n = (lane >> 3) + 8 * j; const LAS float* s = scr + (8 * c) * 33 + n;
;         u32x4 o; o.x = pk2(s[0 * 33], s[1 * 33]); o.y = pk2(s[2 * 33], s[3 * 33]); o.z = pk2(s[4 * 33], s[5 * 33]); o.w = pk2(s[6 * 33], s[7 * 33]);
;         *(u32x4*)(WT + (size_t)(drow0 + n) * K + k0 + 8 * c) = o; }
;     asm volatile("s_waitcnt lgkmcnt(0)" ::: "memory");
	s_waitcnt lgkmcnt(0)
	ds_read2_b32 v[18:19], v20 offset0:33 offset1:41
	ds_read2_b32 v[28:29], v20 offset1:8
	ds_read2_b32 v[30:31], v20 offset0:66 offset1:74
	ds_read2_b32 v[32:33], v20 offset0:99 offset1:107
	ds_read2_b32 v[34:35], v20 offset0:132 offset1:140
	ds_read2_b32 v[36:37], v20 offset0:165 offset1:173
	ds_read2_b32 v[38:39], v20 offset0:198 offset1:206
	ds_read2_b32 v[40:41], v20 offset0:231 offset1:239
	s_mov_b32 s9, s3
	v_or_b32_e32 v2, s2, v5
	v_lshl_add_u64 v[42:43], s[8:9], 1, v[10:11]
	v_lshlrev_b32_e32 v2, 10, v2
	s_waitcnt lgkmcnt(6)
	v_cvt_pk_bf16_f32 v24, v28, v18
	s_waitcnt lgkmcnt(4)
	v_cvt_pk_bf16_f32 v25, v30, v32
	s_waitcnt lgkmcnt(2)
	v_cvt_pk_bf16_f32 v26, v34, v36
	s_waitcnt lgkmcnt(0)
	v_cvt_pk_bf16_f32 v27, v38, v40
	v_lshl_add_u64 v[44:45], v[42:43], 0, v[2:3]
	global_store_dwordx4 v[44:45], v[24:27], off sc1
	v_or_b32_e32 v2, s2, v21
	v_lshlrev_b32_e32 v2, 10, v2
	v_cvt_pk_bf16_f32 v24, v29, v19
	v_cvt_pk_bf16_f32 v25, v31, v33
	v_cvt_pk_bf16_f32 v26, v35, v37
	v_cvt_pk_bf16_f32 v27, v39, v41
	ds_read2_b32 v[28:29], v20 offset0:49 offset1:57
	ds_read2_b32 v[30:31], v20 offset0:16 offset1:24
	ds_read2_b32 v[32:33], v20 offset0:82 offset1:90
	ds_read2_b32 v[34:35], v20 offset0:115 offset1:123
	ds_read2_b32 v[36:37], v20 offset0:148 offset1:156
	ds_read2_b32 v[38:39], v20 offset0:181 offset1:189
	ds_read2_b32 v[40:41], v20 offset0:214 offset1:222
	ds_read2_b32 v[44:45], v20 offset0:247 offset1:255
	v_lshl_add_u64 v[18:19], v[42:43], 0, v[2:3]
	v_or_b32_e32 v2, s2, v22
	v_lshlrev_b32_e32 v2, 10, v2
	global_store_dwordx4 v[18:19], v[24:27], off sc1
	v_lshl_add_u64 v[18:19], v[42:43], 0, v[2:3]
	v_or_b32_e32 v2, s2, v23
	s_waitcnt lgkmcnt(6)
	v_cvt_pk_bf16_f32 v24, v30, v28
	s_waitcnt lgkmcnt(4)
	v_cvt_pk_bf16_f32 v25, v32, v34
	s_waitcnt lgkmcnt(2)
	v_cvt_pk_bf16_f32 v26, v36, v38
	s_waitcnt lgkmcnt(0)
	v_cvt_pk_bf16_f32 v27, v40, v44
	v_lshlrev_b32_e32 v2, 10, v2
	global_store_dwordx4 v[18:19], v[24:27], off sc1
	v_lshl_add_u64 v[18:19], v[42:43], 0, v[2:3]
	s_nop 0
	v_cvt_pk_bf16_f32 v24, v31, v29
	v_cvt_pk_bf16_f32 v25, v33, v35
	v_cvt_pk_bf16_f32 v26, v37, v39
	v_cvt_pk_bf16_f32 v27, v41, v45
	global_store_dwordx4 v[18:19], v[24:27], off sc1
	s_waitcnt lgkmcnt(0)

; #define LAS __attribute__((address_space(3)))
; __device__ __forceinline__ unsigned pk2(float lo, float hi) { f32x2 v = {lo, hi}; bf16x2_t b = __builtin_convertvector(v, bf16x2_t); return __builtin_bit_cast(unsigned, b); }
; __device__ __forceinline__ void transpose_item(const float* W, int K, int N, bf16_t* WT, int k0, int n0, int drow0, LAS float* scr, int lane) {
; #pragma unroll 8
;     for (int i = 0; i < 32; ++i) { const int kk = 2 * i + (lane >> 5); scr[kk * 33 + (lane & 31)] = W[(size_t)(k0 + kk) * N + n0 + (lane & 31)]; }
;     asm volatile("s_waitcnt lgkmcnt(0)" ::: "memory");
;     const int c = lane & 7;
; #pragma unroll
;     for (int j = 0; j < 4; ++j) { const int n = (lane >> 3) + 8 * j; const LAS float* s = scr + (8 * c) * 33 + n;
;         u32x4 o; o.x = pk2(s[0 * 33], s[1 * 33]); o.y = pk2(s[2 * 33], s[3 * 33]); o.z = pk2(s[4 * 33], s[5 * 33]); o.w = pk2(s[6 * 33], s[7 * 33]);
;         *(u32x4*)(WT + (size_t)(drow0 + n) * K + k0 + 8 * c) = o; }
;     asm volatile("s_waitcnt lgkmcnt(0)" ::: "memory");
.LBB0_198:
	s_lshl_b32 s23, s20, 1
	s_lshl_b32 s24, s21, 1
	v_or_b32_e32 v2, s23, v1
	v_or_b32_e32 v17, s24, v0
	s_add_i32 s25, s23, 4
	s_add_i32 s26, s24, 4
	s_add_i32 s27, s23, 8
	s_add_i32 s33, s24, 8
	s_add_i32 s34, s23, 12
	s_add_i32 s35, s24, 12
	s_add_i32 s40, s23, 16
	s_add_i32 s41, s24, 16
	s_add_i32 s42, s23, 20
	s_add_i32 s43, s24, 20
	s_add_i32 s44, s23, 24
	s_add_i32 s45, s24, 24
	s_add_i32 s23, s23, 28
	s_add_i32 s24, s24, 28
	v_add_u32_e32 v24, s2, v17
	v_or_b32_e32 v56, s25, v1
	v_or_b32_e32 v57, s26, v0
	v_or_b32_e32 v58, s27, v1
	v_or_b32_e32 v59, s33, v0
	v_or_b32_e32 v60, s34, v1
	v_or_b32_e32 v61, s35, v0
	v_or_b32_e32 v62, s40, v1
	v_or_b32_e32 v63, s41, v0
	v_or_b32_e32 v64, s42, v1
	v_or_b32_e32 v65, s43, v0
	v_or_b32_e32 v66, s44, v1
	v_or_b32_e32 v67, s45, v0
	v_or_b32_e32 v68, s23, v1
	v_or_b32_e32 v69, s24, v0
	v_add_u32_e32 v26, s19, v2
	v_mad_u64_u32 v[24:25], s[24:25], v24, s17, v[18:19]
	v_add_u32_e32 v30, s19, v56
	v_add_u32_e32 v28, s2, v57
	v_add_u32_e32 v34, s19, v58
	v_add_u32_e32 v32, s2, v59
	v_add_u32_e32 v38, s19, v60
	v_add_u32_e32 v36, s2, v61
	v_add_u32_e32 v42, s19, v62
	v_add_u32_e32 v40, s2, v63
	v_add_u32_e32 v46, s19, v64
	v_add_u32_e32 v44, s2, v65
	v_add_u32_e32 v50, s19, v66
	v_add_u32_e32 v48, s2, v67
	v_add_u32_e32 v54, s19, v68
	v_add_u32_e32 v52, s2, v69
	v_mad_u64_u32 v[26:27], s[24:25], v26, s17, v[18:19]
	v_mad_u64_u32 v[28:29], s[24:25], v28, s17, v[18:19]
	v_mad_u64_u32 v[30:31], s[24:25], v30, s17, v[18:19]
	v_mad_u64_u32 v[32:33], s[24:25], v32, s17, v[18:19]
	v_mad_u64_u32 v[34:35], s[24:25], v34, s17, v[18:19]
	v_mad_u64_u32 v[36:37], s[24:25], v36, s17, v[18:19]
	v_mad_u64_u32 v[38:39], s[24:25], v38, s17, v[18:19]
	v_mad_u64_u32 v[40:41], s[24:25], v40, s17, v[18:19]
	v_mad_u64_u32 v[42:43], s[24:25], v42, s17, v[18:19]
	v_mad_u64_u32 v[44:45], s[24:25], v44, s17, v[18:19]
	v_mad_u64_u32 v[46:47], s[24:25], v46, s17, v[18:19]
	v_mad_u64_u32 v[48:49], s[24:25], v48, s17, v[18:19]
	v_mad_u64_u32 v[50:51], s[24:25], v50, s17, v[18:19]
	v_mad_u64_u32 v[52:53], s[24:25], v52, s17, v[18:19]
	v_mad_u64_u32 v[54:55], s[24:25], v54, s17, v[18:19]
	global_load_dword v70, v[24:25], off
	global_load_dword v71, v[26:27], off
	global_load_dword v72, v[28:29], off
	global_load_dword v73, v[30:31], off
	global_load_dword v74, v[32:33], off
	global_load_dword v75, v[34:35], off
	global_load_dword v76, v[36:37], off
	global_load_dword v77, v[38:39], off
	global_load_dword v78, v[40:41], off
	global_load_dword v79, v[42:43], off
	global_load_dword v80, v[44:45], off
	global_load_dword v81, v[46:47], off
	global_load_dword v82, v[48:49], off
	global_load_dword v83, v[50:51], off
	global_load_dword v84, v[52:53], off
	global_load_dword v85, v[54:55], off
	s_add_i32 s21, s21, 16
	s_add_i32 s20, s20, 16
	s_add_i32 s22, s22, -16
	v_mad_u64_u32 v[24:25], s[24:25], v17, s12, v[4:5]
	s_cmp_lg_u32 s22, 0
	v_mad_u64_u32 v[26:27], s[24:25], v2, s12, v[4:5]
	v_mad_u64_u32 v[28:29], s[24:25], v57, s12, v[4:5]
	v_mad_u64_u32 v[30:31], s[24:25], v56, s12, v[4:5]
	v_mad_u64_u32 v[32:33], s[24:25], v59, s12, v[4:5]
	v_mad_u64_u32 v[34:35], s[24:25], v58, s12, v[4:5]
	v_mad_u64_u32 v[36:37], s[24:25], v61, s12, v[4:5]
	v_mad_u64_u32 v[38:39], s[24:25], v60, s12, v[4:5]
	v_mad_u64_u32 v[40:41], s[24:25], v63, s12, v[4:5]
	v_mad_u64_u32 v[42:43], s[24:25], v62, s12, v[4:5]
	v_mad_u64_u32 v[44:45], s[24:25], v65, s12, v[4:5]
	v_mad_u64_u32 v[46:47], s[24:25], v64, s12, v[4:5]
	v_mad_u64_u32 v[48:49], s[24:25], v67, s12, v[4:5]
	v_mad_u64_u32 v[50:51], s[24:25], v66, s12, v[4:5]
	v_mad_u64_u32 v[52:53], s[24:25], v69, s12, v[4:5]
	v_mad_u64_u32 v[54:55], s[24:25], v68, s12, v[4:5]
	s_waitcnt vmcnt(15)
	ds_write_b32 v24, v70
	s_waitcnt vmcnt(14)
	ds_write_b32 v26, v71
	s_waitcnt vmcnt(13)
	ds_write_b32 v28, v72
	s_waitcnt vmcnt(12)
	ds_write_b32 v30, v73
	s_waitcnt vmcnt(11)
	ds_write_b32 v32, v74
	s_waitcnt vmcnt(10)
	ds_write_b32 v34, v75
	s_waitcnt vmcnt(9)
	ds_write_b32 v36, v76
	s_waitcnt vmcnt(8)
	ds_write_b32 v38, v77
	s_waitcnt vmcnt(7)
	ds_write_b32 v40, v78
	s_waitcnt vmcnt(6)
	ds_write_b32 v42, v79
	s_waitcnt vmcnt(5)
	ds_write_b32 v44, v80
	s_waitcnt vmcnt(4)
	ds_write_b32 v46, v81
	s_waitcnt vmcnt(3)
	ds_write_b32 v48, v82
	s_waitcnt vmcnt(2)
	ds_write_b32 v50, v83
	s_waitcnt vmcnt(1)
	ds_write_b32 v52, v84
	s_waitcnt vmcnt(0)
	ds_write_b32 v54, v85
	s_cbranch_scc1 .LBB0_198
	s_and_b32 s9, 0xffff, s9
	s_lshl_b32 s19, s9, 2
	s_and_b32 s19, s19, 0x80
	s_lshr_b32 s20, s9, 1
	s_and_b32 s21, s9, 0x300
	s_or_b32 s19, s19, s21
	s_and_b32 s20, s20, 0x60
	s_waitcnt lgkmcnt(0)
	s_or_b32 s19, s19, s20
	s_and_b32 s8, 0xffff, s8
	ds_read2_b32 v[18:19], v20 offset0:33 offset1:41
	ds_read2_b32 v[28:29], v20 offset1:8
	ds_read2_b32 v[30:31], v20 offset0:66 offset1:74
	ds_read2_b32 v[32:33], v20 offset0:99 offset1:107
	ds_read2_b32 v[34:35], v20 offset0:132 offset1:140
	ds_read2_b32 v[36:37], v20 offset0:165 offset1:173
	ds_read2_b32 v[38:39], v20 offset0:198 offset1:206
	ds_read2_b32 v[40:41], v20 offset0:231 offset1:239
	s_cmp_lt_u32 s8, 32
	s_cselect_b32 s8, s19, s9
	s_and_b32 s2, 0xffff, s2
	s_lshl_b32 s2, s2, 1
	v_or_b32_e32 v2, s8, v5
	v_lshl_add_u64 v[42:43], v[12:13], 0, s[2:3]
	v_lshlrev_b32_e32 v2, 11, v2
	s_waitcnt lgkmcnt(6)
	v_cvt_pk_bf16_f32 v24, v28, v18
	s_waitcnt lgkmcnt(4)
	v_cvt_pk_bf16_f32 v25, v30, v32
	s_waitcnt lgkmcnt(2)
	v_cvt_pk_bf16_f32 v26, v34, v36
	s_waitcnt lgkmcnt(0)
	v_cvt_pk_bf16_f32 v27, v38, v40
	v_lshl_add_u64 v[44:45], v[42:43], 0, v[2:3]
	global_store_dwordx4 v[44:45], v[24:27], off sc1
	v_or_b32_e32 v2, s8, v21
	v_lshlrev_b32_e32 v2, 11, v2
	v_cvt_pk_bf16_f32 v24, v29, v19
	v_cvt_pk_bf16_f32 v25, v31, v33
	v_cvt_pk_bf16_f32 v26, v35, v37
	v_cvt_pk_bf16_f32 v27, v39, v41
	ds_read2_b32 v[28:29], v20 offset0:49 offset1:57
	ds_read2_b32 v[30:31], v20 offset0:16 offset1:24
	ds_read2_b32 v[32:33], v20 offset0:82 offset1:90
	ds_read2_b32 v[34:35], v20 offset0:115 offset1:123
	ds_read2_b32 v[36:37], v20 offset0:148 offset1:156
	ds_read2_b32 v[38:39], v20 offset0:181 offset1:189
	ds_read2_b32 v[40:41], v20 offset0:214 offset1:222
	ds_read2_b32 v[44:45], v20 offset0:247 offset1:255
	v_lshl_add_u64 v[18:19], v[42:43], 0, v[2:3]
	v_or_b32_e32 v2, s8, v22
	v_lshlrev_b32_e32 v2, 11, v2
	global_store_dwordx4 v[18:19], v[24:27], off sc1
	v_lshl_add_u64 v[18:19], v[42:43], 0, v[2:3]
	v_or_b32_e32 v2, s8, v23
	s_waitcnt lgkmcnt(6)
	v_cvt_pk_bf16_f32 v24, v30, v28
	s_waitcnt lgkmcnt(4)
	v_cvt_pk_bf16_f32 v25, v32, v34
	s_waitcnt lgkmcnt(2)
	v_cvt_pk_bf16_f32 v26, v36, v38
	s_waitcnt lgkmcnt(0)
	v_cvt_pk_bf16_f32 v27, v40, v44
	v_lshlrev_b32_e32 v2, 11, v2
	global_store_dwordx4 v[18:19], v[24:27], off sc1
	v_lshl_add_u64 v[18:19], v[42:43], 0, v[2:3]
	s_nop 0
	v_cvt_pk_bf16_f32 v24, v31, v29
	v_cvt_pk_bf16_f32 v25, v33, v35
	v_cvt_pk_bf16_f32 v26, v37, v39
	v_cvt_pk_bf16_f32 v27, v41, v45
	global_store_dwordx4 v[18:19], v[24:27], off sc1
	s_waitcnt lgkmcnt(0)

; #define LAS __attribute__((address_space(3)))
; __device__ __forceinline__ void transpose_item(const float* W, int K, int N, bf16_t* WT, int k0, int n0, int drow0, LAS float* scr, int lane) {
; #pragma unroll 8
;     for (int i = 0; i < 32; ++i) { const int kk = 2 * i + (lane >> 5); scr[kk * 33 + (lane & 31)] = W[(size_t)(k0 + kk) * N + n0 + (lane & 31)]; }
.LBB0_203:
	s_lshl_b32 s22, s9, 1
	s_lshl_b32 s23, s20, 1
	v_or_b32_e32 v46, s23, v0
	s_add_i32 s24, s22, 4
	s_add_i32 s25, s23, 4
	s_add_i32 s27, s23, 8
	v_add_u32_e32 v2, s2, v46
	v_or_b32_e32 v47, s24, v1
	v_or_b32_e32 v48, s25, v0
	v_mov_b32_e32 v27, v3
	v_or_b32_e32 v17, s22, v1
	s_add_i32 s34, s23, 12
	v_or_b32_e32 v50, s27, v0
	v_lshlrev_b64 v[40:41], 12, v[2:3]
	v_add_u32_e32 v26, s19, v47
	v_add_u32_e32 v2, s2, v48
	v_mov_b32_e32 v25, v3
	s_add_i32 s26, s22, 8
	s_add_i32 s33, s22, 12
	s_add_i32 s40, s23, 16
	v_add_u32_e32 v24, s19, v17
	v_or_b32_e32 v52, s34, v0
	v_lshlrev_b64 v[26:27], 12, v[26:27]
	v_lshlrev_b64 v[42:43], 12, v[2:3]
	v_add_u32_e32 v2, s2, v50
	s_add_i32 s42, s23, 20
	v_or_b32_e32 v49, s26, v1
	v_or_b32_e32 v51, s33, v1
	v_or_b32_e32 v54, s40, v0
	v_lshlrev_b64 v[24:25], 12, v[24:25]
	v_lshl_add_u64 v[40:41], v[18:19], 0, v[40:41]
	v_lshl_add_u64 v[26:27], v[18:19], 0, v[26:27]
	v_lshlrev_b64 v[44:45], 12, v[2:3]
	v_add_u32_e32 v2, s2, v52
	v_mov_b32_e32 v29, v3
	v_mov_b32_e32 v31, v3
	s_add_i32 s35, s22, 16
	s_add_i32 s41, s22, 20
	s_add_i32 s44, s23, 24
	v_or_b32_e32 v56, s42, v0
	v_add_u32_e32 v28, s19, v49
	v_add_u32_e32 v30, s19, v51
	v_lshl_add_u64 v[24:25], v[18:19], 0, v[24:25]
	v_lshl_add_u64 v[42:43], v[18:19], 0, v[42:43]
	global_load_dword v61, v[40:41], off
	global_load_dword v62, v[24:25], off
	global_load_dword v63, v[42:43], off
	global_load_dword v64, v[26:27], off
	v_lshlrev_b64 v[26:27], 12, v[2:3]
	v_add_u32_e32 v2, s2, v54
	s_add_i32 s43, s22, 24
	s_add_i32 s22, s22, 28
	s_add_i32 s23, s23, 28
	v_or_b32_e32 v53, s35, v1
	v_or_b32_e32 v55, s41, v1
	v_or_b32_e32 v58, s44, v0
	v_lshlrev_b64 v[28:29], 12, v[28:29]
	v_lshlrev_b64 v[30:31], 12, v[30:31]
	v_lshl_add_u64 v[24:25], v[18:19], 0, v[44:45]
	v_lshl_add_u64 v[26:27], v[18:19], 0, v[26:27]
	v_lshlrev_b64 v[40:41], 12, v[2:3]
	v_add_u32_e32 v2, s2, v56
	v_mov_b32_e32 v33, v3
	v_mov_b32_e32 v35, v3
	v_or_b32_e32 v57, s43, v1
	v_or_b32_e32 v59, s22, v1
	v_or_b32_e32 v60, s23, v0
	v_add_u32_e32 v32, s19, v53
	v_add_u32_e32 v34, s19, v55
	v_lshl_add_u64 v[28:29], v[18:19], 0, v[28:29]
	v_lshl_add_u64 v[30:31], v[18:19], 0, v[30:31]
	global_load_dword v65, v[24:25], off
	global_load_dword v66, v[28:29], off
	global_load_dword v67, v[26:27], off
	global_load_dword v68, v[30:31], off
	v_lshlrev_b64 v[26:27], 12, v[2:3]
	v_add_u32_e32 v2, s2, v58
	v_mov_b32_e32 v37, v3
	v_mov_b32_e32 v39, v3
	v_add_u32_e32 v36, s19, v57
	v_add_u32_e32 v38, s19, v59
	v_lshlrev_b64 v[32:33], 12, v[32:33]
	v_lshlrev_b64 v[34:35], 12, v[34:35]
	v_lshl_add_u64 v[24:25], v[18:19], 0, v[40:41]
	v_lshl_add_u64 v[26:27], v[18:19], 0, v[26:27]
	v_lshlrev_b64 v[28:29], 12, v[2:3]
	v_add_u32_e32 v2, s2, v60
	v_lshlrev_b64 v[36:37], 12, v[36:37]
	v_lshlrev_b64 v[38:39], 12, v[38:39]
	v_lshl_add_u64 v[32:33], v[18:19], 0, v[32:33]
	v_lshl_add_u64 v[34:35], v[18:19], 0, v[34:35]
	global_load_dword v69, v[24:25], off
	global_load_dword v70, v[32:33], off
	global_load_dword v71, v[26:27], off
	global_load_dword v72, v[34:35], off
	v_lshl_add_u64 v[24:25], v[18:19], 0, v[28:29]
	v_lshlrev_b64 v[26:27], 12, v[2:3]
	v_lshl_add_u64 v[36:37], v[18:19], 0, v[36:37]
	v_lshl_add_u64 v[38:39], v[18:19], 0, v[38:39]
	v_lshl_add_u64 v[26:27], v[18:19], 0, v[26:27]
	global_load_dword v2, v[24:25], off
	global_load_dword v73, v[36:37], off
	global_load_dword v74, v[26:27], off
	global_load_dword v75, v[38:39], off
	s_add_i32 s20, s20, 16
	s_add_i32 s9, s9, 16
	s_add_i32 s21, s21, -16
	v_mad_u64_u32 v[24:25], s[22:23], v46, s12, v[4:5]
	s_cmp_lg_u32 s21, 0
	v_mad_u64_u32 v[26:27], s[22:23], v17, s12, v[4:5]
	v_mad_u64_u32 v[28:29], s[22:23], v48, s12, v[4:5]
	v_mad_u64_u32 v[30:31], s[22:23], v47, s12, v[4:5]
	v_mad_u64_u32 v[32:33], s[22:23], v50, s12, v[4:5]
	v_mad_u64_u32 v[34:35], s[22:23], v49, s12, v[4:5]
	v_mad_u64_u32 v[36:37], s[22:23], v52, s12, v[4:5]
	v_mad_u64_u32 v[38:39], s[22:23], v51, s12, v[4:5]
	v_mad_u64_u32 v[40:41], s[22:23], v54, s12, v[4:5]
	v_mad_u64_u32 v[42:43], s[22:23], v53, s12, v[4:5]
	v_mad_u64_u32 v[44:45], s[22:23], v56, s12, v[4:5]
	v_mad_u64_u32 v[46:47], s[22:23], v55, s12, v[4:5]
	v_mad_u64_u32 v[48:49], s[22:23], v58, s12, v[4:5]
	v_mad_u64_u32 v[50:51], s[22:23], v57, s12, v[4:5]
	v_mad_u64_u32 v[52:53], s[22:23], v60, s12, v[4:5]
	v_mad_u64_u32 v[54:55], s[22:23], v59, s12, v[4:5]
	s_waitcnt vmcnt(15)
	ds_write_b32 v24, v61
	s_waitcnt vmcnt(14)
	ds_write_b32 v26, v62
	s_waitcnt vmcnt(13)
	ds_write_b32 v28, v63
	s_waitcnt vmcnt(12)
	ds_write_b32 v30, v64
	s_waitcnt vmcnt(11)
	ds_write_b32 v32, v65
	s_waitcnt vmcnt(10)
	ds_write_b32 v34, v66
	s_waitcnt vmcnt(9)
	ds_write_b32 v36, v67
	s_waitcnt vmcnt(8)
	ds_write_b32 v38, v68
	s_waitcnt vmcnt(7)
	ds_write_b32 v40, v69
	s_waitcnt vmcnt(6)
	ds_write_b32 v42, v70
	s_waitcnt vmcnt(5)
	ds_write_b32 v44, v71
	s_waitcnt vmcnt(4)
	ds_write_b32 v46, v72
	s_waitcnt vmcnt(3)
	ds_write_b32 v48, v2
	s_waitcnt vmcnt(2)
	ds_write_b32 v50, v73
	s_waitcnt vmcnt(1)
	ds_write_b32 v52, v74
	s_waitcnt vmcnt(0)
	ds_write_b32 v54, v75
	s_cbranch_scc1 .LBB0_203
; #define LAS __attribute__((address_space(3)))
; __device__ __forceinline__ unsigned pk2(float lo, float hi) { f32x2 v = {lo, hi}; bf16x2_t b = __builtin_convertvector(v, bf16x2_t); return __builtin_bit_cast(unsigned, b); }
; __device__ __forceinline__ void transpose_item(const float* W, int K, int N, bf16_t* WT, int k0, int n0, int drow0, LAS float* scr, int lane) {
;     ...
;     asm volatile("s_waitcnt lgkmcnt(0)" ::: "memory");
;     const int c = lane & 7;
; #pragma unroll
;     for (int j = 0; j < 4; ++j) { const int n = (lane >> 3) + 8 * j; const LAS float* s = scr + (8 * c) * 33 + n;
;         u32x4 o; o.x = pk2(s[0 * 33], s[1 * 33]); o.y = pk2(s[2 * 33], s[3 * 33]); o.z = pk2(s[4 * 33], s[5 * 33]); o.w = pk2(s[6 * 33], s[7 * 33]);
;         *(u32x4*)(WT + (size_t)(drow0 + n) * K + k0 + 8 * c) = o; }
;     asm volatile("s_waitcnt lgkmcnt(0)" ::: "memory");
	s_waitcnt lgkmcnt(0)
	ds_read2_b32 v[18:19], v20 offset0:33 offset1:41
	ds_read2_b32 v[28:29], v20 offset1:8
	ds_read2_b32 v[30:31], v20 offset0:66 offset1:74
	ds_read2_b32 v[32:33], v20 offset0:99 offset1:107
	ds_read2_b32 v[34:35], v20 offset0:132 offset1:140
	ds_read2_b32 v[36:37], v20 offset0:165 offset1:173
	ds_read2_b32 v[38:39], v20 offset0:198 offset1:206
	ds_read2_b32 v[40:41], v20 offset0:231 offset1:239
	v_or_b32_e32 v2, s8, v5
	s_lshl_b32 s2, s2, 1
	v_mul_u32_u24_e32 v2, 0xb00, v2
	v_lshl_add_u64 v[42:43], v[14:15], 0, s[2:3]
	v_lshlrev_b32_e32 v2, 1, v2
	v_lshl_add_u64 v[44:45], v[42:43], 0, v[2:3]
	v_or_b32_e32 v2, s8, v21
	s_waitcnt lgkmcnt(6)
	v_cvt_pk_bf16_f32 v24, v28, v18
	s_waitcnt lgkmcnt(4)
	v_cvt_pk_bf16_f32 v25, v30, v32
	s_waitcnt lgkmcnt(2)
	v_cvt_pk_bf16_f32 v26, v34, v36
	s_waitcnt lgkmcnt(0)
	v_cvt_pk_bf16_f32 v27, v38, v40
	v_mul_u32_u24_e32 v2, 0xb00, v2
	global_store_dwordx4 v[44:45], v[24:27], off sc1
	v_lshlrev_b32_e32 v2, 1, v2
	s_nop 0
	v_cvt_pk_bf16_f32 v24, v29, v19
	v_cvt_pk_bf16_f32 v25, v31, v33
	v_cvt_pk_bf16_f32 v26, v35, v37
	v_cvt_pk_bf16_f32 v27, v39, v41
	v_lshl_add_u64 v[18:19], v[42:43], 0, v[2:3]
	ds_read2_b32 v[28:29], v20 offset0:16 offset1:24
	ds_read2_b32 v[30:31], v20 offset0:49 offset1:57
	ds_read2_b32 v[32:33], v20 offset0:82 offset1:90
	ds_read2_b32 v[34:35], v20 offset0:115 offset1:123
	ds_read2_b32 v[36:37], v20 offset0:148 offset1:156
	ds_read2_b32 v[38:39], v20 offset0:181 offset1:189
	ds_read2_b32 v[40:41], v20 offset0:214 offset1:222
	ds_read2_b32 v[44:45], v20 offset0:247 offset1:255
	v_or_b32_e32 v2, s8, v22
	v_mul_u32_u24_e32 v2, 0xb00, v2
	v_lshlrev_b32_e32 v2, 1, v2
	global_store_dwordx4 v[18:19], v[24:27], off sc1
	v_lshl_add_u64 v[18:19], v[42:43], 0, v[2:3]
	v_or_b32_e32 v2, s8, v23
	v_mul_u32_u24_e32 v2, 0xb00, v2
	s_waitcnt lgkmcnt(6)
	v_cvt_pk_bf16_f32 v24, v28, v30
	s_waitcnt lgkmcnt(4)
	v_cvt_pk_bf16_f32 v25, v32, v34
	s_waitcnt lgkmcnt(2)
	v_cvt_pk_bf16_f32 v26, v36, v38
	s_waitcnt lgkmcnt(0)
	v_cvt_pk_bf16_f32 v27, v40, v44
	v_lshlrev_b32_e32 v2, 1, v2
	global_store_dwordx4 v[18:19], v[24:27], off sc1
	v_lshl_add_u64 v[18:19], v[42:43], 0, v[2:3]
	s_nop 0
	v_cvt_pk_bf16_f32 v24, v29, v31
	v_cvt_pk_bf16_f32 v25, v33, v35
	v_cvt_pk_bf16_f32 v26, v37, v39
	v_cvt_pk_bf16_f32 v27, v41, v45
	global_store_dwordx4 v[18:19], v[24:27], off sc1
	s_waitcnt lgkmcnt(0)
	s_branch .LBB0_178

; __device__ __forceinline__ unsigned pk2(float lo, float hi) { f32x2 v = {lo, hi}; bf16x2_t b = __builtin_convertvector(v, bf16x2_t); return __builtin_bit_cast(unsigned, b); }
; __device__ __forceinline__ float sigmoidf_(float x) { return frcp(1.f + fexp2(-1.4426950408889634f * x)); }
;     __device__ __forceinline__ void operator()(const f32x4 (&acc)[2][2][4][2], const Unit& u, int wr, int wc, int fr, int fq) const {
;         const int col0 = u.pn * 128 + wc * 32 + 8 * fq;
; #pragma unroll
;         for (int ai = 0; ai < 2; ++ai)
; #pragma unroll
;             for (int m = 0; m < 4; ++m) {
;                 const int row = u.pm * 256 + ai * 128 + wr * 64 + m * 16 + fr;
;                 float v[8];
; #pragma unroll
;                 for (int n = 0; n < 2; ++n)
; #pragma unroll
;                     for (int i = 0; i < 4; ++i) { const float g = acc[ai][0][m][n][i], up = acc[ai][1][m][n][i]; v[n * 4 + i] = g * sigmoidf_(g) * up; }
;                 u32x4 w; w.x = pk2(v[0], v[1]); w.y = pk2(v[2], v[3]); w.z = pk2(v[4], v[5]); w.w = pk2(v[6], v[7]);
;                 if (row < MR) *(u32x4*)(O + (size_t)row * DFF + col0) = w;
;                 asm volatile("" ::: "memory");
;             }
;     }
.LBB0_2331:
	s_lshl_b32 s15, s22, 8
	v_lshl_or_b32 v144, s24, 7, v151
	v_add_u32_e32 v155, s15, v146
	v_ashrrev_i32_e32 v145, 31, v144
	v_cmp_gt_i32_e32 vcc, s57, v155
	s_and_saveexec_b64 s[22:23], vcc
	s_cbranch_execz .LBB0_2333
	v_mul_f32_e32 v156, 0xbfb8aa3b, v124
	v_mul_f32_e32 v157, 0xbfb8aa3b, v125
	v_exp_f32_e32 v156, v156
	v_exp_f32_e32 v157, v157
	v_mul_f32_e32 v158, 0xbfb8aa3b, v126
	v_exp_f32_e32 v158, v158
	v_add_f32_e32 v156, 1.0, v156
	v_add_f32_e32 v157, 1.0, v157
	v_rcp_f32_e32 v156, v156
	v_rcp_f32_e32 v157, v157
	s_nop 0
	v_pk_mul_f32 v[124:125], v[124:125], v[156:157]
	v_mul_f32_e32 v156, 0xbfb8aa3b, v127
	v_exp_f32_e32 v156, v156
	v_pk_mul_f32 v[116:117], v[124:125], v[116:117]
	v_add_f32_e32 v124, 1.0, v158
	v_mul_f32_e32 v157, 0xbfb8aa3b, v121
	v_add_f32_e32 v125, 1.0, v156
	v_mul_f32_e32 v156, 0xbfb8aa3b, v120
	v_rcp_f32_e32 v124, v124
	v_rcp_f32_e32 v125, v125
	v_exp_f32_e32 v156, v156
	v_exp_f32_e32 v157, v157
	v_pk_mul_f32 v[124:125], v[126:127], v[124:125]
	v_add_f32_e32 v126, 1.0, v156
	v_add_f32_e32 v127, 1.0, v157
	v_mul_f32_e32 v156, 0xbfb8aa3b, v122
	v_mul_f32_e32 v157, 0xbfb8aa3b, v123
	v_exp_f32_e32 v156, v156
	v_exp_f32_e32 v157, v157
	v_rcp_f32_e32 v126, v126
	v_rcp_f32_e32 v127, v127
	v_add_f32_e32 v156, 1.0, v156
	v_add_f32_e32 v157, 1.0, v157
	v_rcp_f32_e32 v156, v156
	v_rcp_f32_e32 v157, v157
	v_pk_mul_f32 v[120:121], v[120:121], v[126:127]
	v_pk_mul_f32 v[118:119], v[124:125], v[118:119]
	v_pk_mul_f32 v[112:113], v[120:121], v[112:113]
	v_pk_mul_f32 v[120:121], v[122:123], v[156:157]
	s_nop 0
	v_pk_mul_f32 v[114:115], v[120:121], v[114:115]
	s_nop 0
	v_cvt_pk_bf16_f32 v115, v114, v115
	v_cvt_pk_bf16_f32 v114, v112, v113
	v_cvt_pk_bf16_f32 v112, v116, v117
	v_mov_b64_e32 v[116:117], s[8:9]
	v_mad_i64_i32 v[116:117], s[26:27], v155, s58, v[116:117]
	v_cvt_pk_bf16_f32 v113, v118, v119
	v_lshl_add_u64 v[116:117], v[144:145], 1, v[116:117]
	global_store_dwordx4 v[116:117], v[112:115], off sc1
.LBB0_2333:
	s_or_b64 exec, exec, s[22:23]
	s_nop 0
	v_add_u32_e32 v112, s15, v148
	v_cmp_gt_i32_e32 vcc, s57, v112
	s_and_saveexec_b64 s[22:23], vcc
	s_cbranch_execz .LBB0_2335
	v_mul_f32_e32 v113, 0xbfb8aa3b, v108
	v_mul_f32_e32 v114, 0xbfb8aa3b, v109
	v_exp_f32_e32 v113, v113
	v_exp_f32_e32 v114, v114
	v_add_f32_e32 v113, 1.0, v113
	v_add_f32_e32 v115, 1.0, v114
	v_rcp_f32_e32 v114, v113
	v_rcp_f32_e32 v115, v115
	v_mul_f32_e32 v113, 0xbfb8aa3b, v110
	v_exp_f32_e32 v113, v113
	v_pk_mul_f32 v[108:109], v[108:109], v[114:115]
	v_mul_f32_e32 v114, 0xbfb8aa3b, v111
	v_exp_f32_e32 v114, v114
	v_pk_mul_f32 v[100:101], v[108:109], v[100:101]
	v_add_f32_e32 v108, 1.0, v113
	v_mul_f32_e32 v113, 0xbfb8aa3b, v104
	v_add_f32_e32 v109, 1.0, v114
	v_rcp_f32_e32 v108, v108
	v_rcp_f32_e32 v109, v109
	v_exp_f32_e32 v113, v113
	v_mul_f32_e32 v114, 0xbfb8aa3b, v105
	v_exp_f32_e32 v114, v114
	v_pk_mul_f32 v[108:109], v[110:111], v[108:109]
	v_add_f32_e32 v110, 1.0, v113
	v_mul_f32_e32 v113, 0xbfb8aa3b, v106
	v_add_f32_e32 v111, 1.0, v114
	v_exp_f32_e32 v113, v113
	v_mul_f32_e32 v114, 0xbfb8aa3b, v107
	v_exp_f32_e32 v115, v114
	v_rcp_f32_e32 v110, v110
	v_add_f32_e32 v113, 1.0, v113
	v_rcp_f32_e32 v111, v111
	v_rcp_f32_e32 v114, v113
	v_add_f32_e32 v113, 1.0, v115
	v_rcp_f32_e32 v115, v113
	v_pk_mul_f32 v[104:105], v[104:105], v[110:111]
	v_pk_mul_f32 v[102:103], v[108:109], v[102:103]
	v_pk_mul_f32 v[96:97], v[104:105], v[96:97]
	v_pk_mul_f32 v[104:105], v[106:107], v[114:115]
	s_nop 0
	v_pk_mul_f32 v[98:99], v[104:105], v[98:99]
	s_nop 0
	v_cvt_pk_bf16_f32 v99, v98, v99
	v_cvt_pk_bf16_f32 v98, v96, v97
	v_cvt_pk_bf16_f32 v96, v100, v101
	v_mov_b64_e32 v[100:101], s[8:9]
	v_mad_i64_i32 v[100:101], s[26:27], v112, s58, v[100:101]
	v_cvt_pk_bf16_f32 v97, v102, v103
	v_lshl_add_u64 v[100:101], v[144:145], 1, v[100:101]
	global_store_dwordx4 v[100:101], v[96:99], off sc1
.LBB0_2335:
	s_or_b64 exec, exec, s[22:23]
	s_nop 0
	v_add_u32_e32 v96, s15, v149
	v_cmp_gt_i32_e32 vcc, s57, v96
	s_and_saveexec_b64 s[22:23], vcc
	s_cbranch_execz .LBB0_2337
	v_mul_f32_e32 v97, 0xbfb8aa3b, v92
	v_mul_f32_e32 v98, 0xbfb8aa3b, v93
	v_exp_f32_e32 v97, v97
	v_exp_f32_e32 v98, v98
	v_add_f32_e32 v97, 1.0, v97
	v_add_f32_e32 v99, 1.0, v98
	v_rcp_f32_e32 v98, v97
	v_rcp_f32_e32 v99, v99
	v_mul_f32_e32 v97, 0xbfb8aa3b, v94
	v_exp_f32_e32 v97, v97
	v_pk_mul_f32 v[92:93], v[92:93], v[98:99]
	v_mul_f32_e32 v98, 0xbfb8aa3b, v95
	v_exp_f32_e32 v98, v98
	v_pk_mul_f32 v[84:85], v[92:93], v[84:85]
	v_add_f32_e32 v92, 1.0, v97
	v_mul_f32_e32 v97, 0xbfb8aa3b, v88
	v_add_f32_e32 v93, 1.0, v98
	v_rcp_f32_e32 v92, v92
	v_rcp_f32_e32 v93, v93
	v_exp_f32_e32 v97, v97
	v_mul_f32_e32 v98, 0xbfb8aa3b, v89
	v_exp_f32_e32 v98, v98
	v_pk_mul_f32 v[92:93], v[94:95], v[92:93]
	v_add_f32_e32 v94, 1.0, v97
	v_mul_f32_e32 v97, 0xbfb8aa3b, v90
	v_add_f32_e32 v95, 1.0, v98
	v_exp_f32_e32 v97, v97
	v_mul_f32_e32 v98, 0xbfb8aa3b, v91
	v_exp_f32_e32 v99, v98
	v_rcp_f32_e32 v94, v94
	v_add_f32_e32 v97, 1.0, v97
	v_rcp_f32_e32 v95, v95
	v_rcp_f32_e32 v98, v97
	v_add_f32_e32 v97, 1.0, v99
	v_rcp_f32_e32 v99, v97
	v_pk_mul_f32 v[88:89], v[88:89], v[94:95]
	v_pk_mul_f32 v[86:87], v[92:93], v[86:87]
	v_pk_mul_f32 v[80:81], v[88:89], v[80:81]
	v_pk_mul_f32 v[88:89], v[90:91], v[98:99]
	s_nop 0
	v_pk_mul_f32 v[82:83], v[88:89], v[82:83]
	s_nop 0
	v_cvt_pk_bf16_f32 v83, v82, v83
	v_cvt_pk_bf16_f32 v82, v80, v81
	v_cvt_pk_bf16_f32 v80, v84, v85
	v_mov_b64_e32 v[84:85], s[8:9]
	v_mad_i64_i32 v[84:85], s[26:27], v96, s58, v[84:85]
	v_cvt_pk_bf16_f32 v81, v86, v87
	v_lshl_add_u64 v[84:85], v[144:145], 1, v[84:85]
	global_store_dwordx4 v[84:85], v[80:83], off sc1
; __device__ __forceinline__ unsigned pk2(float lo, float hi) { f32x2 v = {lo, hi}; bf16x2_t b = __builtin_convertvector(v, bf16x2_t); return __builtin_bit_cast(unsigned, b); }
; __device__ __forceinline__ float sigmoidf_(float x) { return frcp(1.f + fexp2(-1.4426950408889634f * x)); }
;     __device__ __forceinline__ void operator()(const f32x4 (&acc)[2][2][4][2], const Unit& u, int wr, int wc, int fr, int fq) const {
;         const int col0 = u.pn * 128 + wc * 32 + 8 * fq;
; #pragma unroll
;         for (int ai = 0; ai < 2; ++ai)
; #pragma unroll
;             for (int m = 0; m < 4; ++m) {
;                 const int row = u.pm * 256 + ai * 128 + wr * 64 + m * 16 + fr;
;                 float v[8];
; #pragma unroll
;                 for (int n = 0; n < 2; ++n)
; #pragma unroll
;                     for (int i = 0; i < 4; ++i) { const float g = acc[ai][0][m][n][i], up = acc[ai][1][m][n][i]; v[n * 4 + i] = g * sigmoidf_(g) * up; }
;                 u32x4 w; w.x = pk2(v[0], v[1]); w.y = pk2(v[2], v[3]); w.z = pk2(v[4], v[5]); w.w = pk2(v[6], v[7]);
;                 if (row < MR) *(u32x4*)(O + (size_t)row * DFF + col0) = w;
;                 asm volatile("" ::: "memory");
;             }
;     }
.LBB0_2337:
	s_or_b64 exec, exec, s[22:23]
	s_nop 0
	v_add_u32_e32 v80, s15, v150
	v_cmp_gt_i32_e32 vcc, s57, v80
	s_and_saveexec_b64 s[22:23], vcc
	s_cbranch_execz .LBB0_2339
	v_mul_f32_e32 v81, 0xbfb8aa3b, v76
	v_mul_f32_e32 v82, 0xbfb8aa3b, v77
	v_exp_f32_e32 v81, v81
	v_exp_f32_e32 v82, v82
	v_add_f32_e32 v81, 1.0, v81
	v_add_f32_e32 v83, 1.0, v82
	v_rcp_f32_e32 v82, v81
	v_rcp_f32_e32 v83, v83
	v_mul_f32_e32 v81, 0xbfb8aa3b, v78
	v_exp_f32_e32 v81, v81
	v_pk_mul_f32 v[76:77], v[76:77], v[82:83]
	v_mul_f32_e32 v82, 0xbfb8aa3b, v79
	v_exp_f32_e32 v82, v82
	v_pk_mul_f32 v[68:69], v[76:77], v[68:69]
	v_add_f32_e32 v76, 1.0, v81
	v_mul_f32_e32 v81, 0xbfb8aa3b, v72
	v_add_f32_e32 v77, 1.0, v82
	v_rcp_f32_e32 v76, v76
	v_rcp_f32_e32 v77, v77
	v_exp_f32_e32 v81, v81
	v_mul_f32_e32 v82, 0xbfb8aa3b, v73
	v_exp_f32_e32 v82, v82
	v_pk_mul_f32 v[76:77], v[78:79], v[76:77]
	v_add_f32_e32 v78, 1.0, v81
	v_mul_f32_e32 v81, 0xbfb8aa3b, v74
	v_add_f32_e32 v79, 1.0, v82
	v_exp_f32_e32 v81, v81
	v_mul_f32_e32 v82, 0xbfb8aa3b, v75
	v_exp_f32_e32 v83, v82
	v_rcp_f32_e32 v78, v78
	v_add_f32_e32 v81, 1.0, v81
	v_rcp_f32_e32 v79, v79
	v_rcp_f32_e32 v82, v81
	v_add_f32_e32 v81, 1.0, v83
	v_rcp_f32_e32 v83, v81
	v_pk_mul_f32 v[72:73], v[72:73], v[78:79]
	v_pk_mul_f32 v[70:71], v[76:77], v[70:71]
	v_pk_mul_f32 v[64:65], v[72:73], v[64:65]
	v_pk_mul_f32 v[72:73], v[74:75], v[82:83]
	s_nop 0
	v_pk_mul_f32 v[66:67], v[72:73], v[66:67]
	s_nop 0
	v_cvt_pk_bf16_f32 v67, v66, v67
	v_cvt_pk_bf16_f32 v66, v64, v65
	v_cvt_pk_bf16_f32 v64, v68, v69
	v_mov_b64_e32 v[68:69], s[8:9]
	v_mad_i64_i32 v[68:69], s[26:27], v80, s58, v[68:69]
	v_cvt_pk_bf16_f32 v65, v70, v71
	v_lshl_add_u64 v[68:69], v[144:145], 1, v[68:69]
	global_store_dwordx4 v[68:69], v[64:67], off sc1
.LBB0_2339:
	s_or_b64 exec, exec, s[22:23]
	s_nop 0
	v_add_u32_e32 v64, 0x80, v155
	v_cmp_gt_i32_e32 vcc, s57, v64
	s_and_saveexec_b64 s[22:23], vcc
	s_cbranch_execz .LBB0_2341
	v_mul_f32_e32 v65, 0xbfb8aa3b, v60
	v_mul_f32_e32 v66, 0xbfb8aa3b, v61
	v_exp_f32_e32 v65, v65
	v_exp_f32_e32 v66, v66
	v_add_f32_e32 v65, 1.0, v65
	v_add_f32_e32 v67, 1.0, v66
	v_rcp_f32_e32 v66, v65
	v_rcp_f32_e32 v67, v67
	v_mul_f32_e32 v65, 0xbfb8aa3b, v62
	v_exp_f32_e32 v65, v65
	v_pk_mul_f32 v[60:61], v[60:61], v[66:67]
	v_mul_f32_e32 v66, 0xbfb8aa3b, v63
	v_exp_f32_e32 v66, v66
	v_pk_mul_f32 v[52:53], v[60:61], v[52:53]
	v_add_f32_e32 v60, 1.0, v65
	v_mul_f32_e32 v65, 0xbfb8aa3b, v56
	v_add_f32_e32 v61, 1.0, v66
	v_rcp_f32_e32 v60, v60
	v_rcp_f32_e32 v61, v61
	v_exp_f32_e32 v65, v65
	v_mul_f32_e32 v66, 0xbfb8aa3b, v57
	v_exp_f32_e32 v66, v66
	v_pk_mul_f32 v[60:61], v[62:63], v[60:61]
	v_add_f32_e32 v62, 1.0, v65
	v_mul_f32_e32 v65, 0xbfb8aa3b, v58
	v_add_f32_e32 v63, 1.0, v66
	v_exp_f32_e32 v65, v65
	v_mul_f32_e32 v66, 0xbfb8aa3b, v59
	v_exp_f32_e32 v67, v66
	v_rcp_f32_e32 v62, v62
	v_add_f32_e32 v65, 1.0, v65
	v_rcp_f32_e32 v63, v63
	v_rcp_f32_e32 v66, v65
	v_add_f32_e32 v65, 1.0, v67
	v_rcp_f32_e32 v67, v65
	v_pk_mul_f32 v[56:57], v[56:57], v[62:63]
	v_pk_mul_f32 v[54:55], v[60:61], v[54:55]
	v_pk_mul_f32 v[48:49], v[56:57], v[48:49]
	v_pk_mul_f32 v[56:57], v[58:59], v[66:67]
	s_nop 0
	v_pk_mul_f32 v[50:51], v[56:57], v[50:51]
	s_nop 0
	v_cvt_pk_bf16_f32 v51, v50, v51
	v_cvt_pk_bf16_f32 v50, v48, v49
	v_cvt_pk_bf16_f32 v48, v52, v53
	v_mov_b64_e32 v[52:53], s[8:9]
	v_mad_i64_i32 v[52:53], s[26:27], v64, s58, v[52:53]
	v_cvt_pk_bf16_f32 v49, v54, v55
	v_lshl_add_u64 v[52:53], v[144:145], 1, v[52:53]
	global_store_dwordx4 v[52:53], v[48:51], off sc1
; __device__ __forceinline__ unsigned pk2(float lo, float hi) { f32x2 v = {lo, hi}; bf16x2_t b = __builtin_convertvector(v, bf16x2_t); return __builtin_bit_cast(unsigned, b); }
; __device__ __forceinline__ float sigmoidf_(float x) { return frcp(1.f + fexp2(-1.4426950408889634f * x)); }
;     __device__ __forceinline__ void operator()(const f32x4 (&acc)[2][2][4][2], const Unit& u, int wr, int wc, int fr, int fq) const {
;         const int col0 = u.pn * 128 + wc * 32 + 8 * fq;
; #pragma unroll
;         for (int ai = 0; ai < 2; ++ai)
; #pragma unroll
;             for (int m = 0; m < 4; ++m) {
;                 const int row = u.pm * 256 + ai * 128 + wr * 64 + m * 16 + fr;
;                 float v[8];
; #pragma unroll
;                 for (int n = 0; n < 2; ++n)
; #pragma unroll
;                     for (int i = 0; i < 4; ++i) { const float g = acc[ai][0][m][n][i], up = acc[ai][1][m][n][i]; v[n * 4 + i] = g * sigmoidf_(g) * up; }
;                 u32x4 w; w.x = pk2(v[0], v[1]); w.y = pk2(v[2], v[3]); w.z = pk2(v[4], v[5]); w.w = pk2(v[6], v[7]);
;                 if (row < MR) *(u32x4*)(O + (size_t)row * DFF + col0) = w;
;                 asm volatile("" ::: "memory");
;             }
;     }
.LBB0_2341:
	s_or_b64 exec, exec, s[22:23]
	s_nop 0
	v_add_u32_e32 v48, 0x90, v155
	v_cmp_gt_i32_e32 vcc, s57, v48
	s_and_saveexec_b64 s[22:23], vcc
	s_cbranch_execz .LBB0_2343
	v_mul_f32_e32 v49, 0xbfb8aa3b, v44
	v_mul_f32_e32 v50, 0xbfb8aa3b, v45
	v_exp_f32_e32 v49, v49
	v_exp_f32_e32 v50, v50
	v_add_f32_e32 v49, 1.0, v49
	v_add_f32_e32 v51, 1.0, v50
	v_rcp_f32_e32 v50, v49
	v_rcp_f32_e32 v51, v51
	v_mul_f32_e32 v49, 0xbfb8aa3b, v46
	v_exp_f32_e32 v49, v49
	v_pk_mul_f32 v[44:45], v[44:45], v[50:51]
	v_mul_f32_e32 v50, 0xbfb8aa3b, v47
	v_exp_f32_e32 v50, v50
	v_pk_mul_f32 v[36:37], v[44:45], v[36:37]
	v_add_f32_e32 v44, 1.0, v49
	v_mul_f32_e32 v49, 0xbfb8aa3b, v40
	v_add_f32_e32 v45, 1.0, v50
	v_rcp_f32_e32 v44, v44
	v_rcp_f32_e32 v45, v45
	v_exp_f32_e32 v49, v49
	v_mul_f32_e32 v50, 0xbfb8aa3b, v41
	v_exp_f32_e32 v50, v50
	v_pk_mul_f32 v[44:45], v[46:47], v[44:45]
	v_add_f32_e32 v46, 1.0, v49
	v_mul_f32_e32 v49, 0xbfb8aa3b, v42
	v_add_f32_e32 v47, 1.0, v50
	v_exp_f32_e32 v49, v49
	v_mul_f32_e32 v50, 0xbfb8aa3b, v43
	v_exp_f32_e32 v51, v50
	v_rcp_f32_e32 v46, v46
	v_add_f32_e32 v49, 1.0, v49
	v_rcp_f32_e32 v47, v47
	v_rcp_f32_e32 v50, v49
	v_add_f32_e32 v49, 1.0, v51
	v_rcp_f32_e32 v51, v49
	v_pk_mul_f32 v[40:41], v[40:41], v[46:47]
	v_pk_mul_f32 v[38:39], v[44:45], v[38:39]
	v_pk_mul_f32 v[32:33], v[40:41], v[32:33]
	v_pk_mul_f32 v[40:41], v[42:43], v[50:51]
	s_nop 0
	v_pk_mul_f32 v[34:35], v[40:41], v[34:35]
	s_nop 0
	v_cvt_pk_bf16_f32 v35, v34, v35
	v_cvt_pk_bf16_f32 v34, v32, v33
	v_cvt_pk_bf16_f32 v32, v36, v37
	v_mov_b64_e32 v[36:37], s[8:9]
	v_mad_i64_i32 v[36:37], s[26:27], v48, s58, v[36:37]
	v_cvt_pk_bf16_f32 v33, v38, v39
	v_lshl_add_u64 v[36:37], v[144:145], 1, v[36:37]
	global_store_dwordx4 v[36:37], v[32:35], off sc1
.LBB0_2343:
	s_or_b64 exec, exec, s[22:23]
	s_nop 0
	v_add_u32_e32 v32, 0xa0, v155
	v_cmp_gt_i32_e32 vcc, s57, v32
	s_and_saveexec_b64 s[22:23], vcc
	s_cbranch_execz .LBB0_2345
	v_mul_f32_e32 v33, 0xbfb8aa3b, v28
	v_mul_f32_e32 v34, 0xbfb8aa3b, v29
	v_exp_f32_e32 v33, v33
	v_exp_f32_e32 v34, v34
	v_add_f32_e32 v33, 1.0, v33
	v_add_f32_e32 v35, 1.0, v34
	v_rcp_f32_e32 v34, v33
	v_rcp_f32_e32 v35, v35
	v_mul_f32_e32 v33, 0xbfb8aa3b, v30
	v_exp_f32_e32 v33, v33
	v_pk_mul_f32 v[28:29], v[28:29], v[34:35]
	v_mul_f32_e32 v34, 0xbfb8aa3b, v31
	v_exp_f32_e32 v34, v34
	v_pk_mul_f32 v[20:21], v[28:29], v[20:21]
	v_add_f32_e32 v28, 1.0, v33
	v_mul_f32_e32 v33, 0xbfb8aa3b, v24
	v_add_f32_e32 v29, 1.0, v34
	v_rcp_f32_e32 v28, v28
	v_rcp_f32_e32 v29, v29
	v_exp_f32_e32 v33, v33
	v_mul_f32_e32 v34, 0xbfb8aa3b, v25
	v_exp_f32_e32 v34, v34
	v_pk_mul_f32 v[28:29], v[30:31], v[28:29]
	v_add_f32_e32 v30, 1.0, v33
	v_mul_f32_e32 v33, 0xbfb8aa3b, v26
	v_add_f32_e32 v31, 1.0, v34
	v_exp_f32_e32 v33, v33
	v_mul_f32_e32 v34, 0xbfb8aa3b, v27
	v_exp_f32_e32 v35, v34
	v_rcp_f32_e32 v30, v30
	v_add_f32_e32 v33, 1.0, v33
	v_rcp_f32_e32 v31, v31
	v_rcp_f32_e32 v34, v33
	v_add_f32_e32 v33, 1.0, v35
	v_rcp_f32_e32 v35, v33
	v_pk_mul_f32 v[24:25], v[24:25], v[30:31]
	v_pk_mul_f32 v[22:23], v[28:29], v[22:23]
	v_pk_mul_f32 v[16:17], v[24:25], v[16:17]
	v_pk_mul_f32 v[24:25], v[26:27], v[34:35]
	s_nop 0
	v_pk_mul_f32 v[18:19], v[24:25], v[18:19]
	s_nop 0
	v_cvt_pk_bf16_f32 v19, v18, v19
	v_cvt_pk_bf16_f32 v18, v16, v17
	v_cvt_pk_bf16_f32 v16, v20, v21
	v_mov_b64_e32 v[20:21], s[8:9]
	v_mad_i64_i32 v[20:21], s[26:27], v32, s58, v[20:21]
	v_cvt_pk_bf16_f32 v17, v22, v23
	v_lshl_add_u64 v[20:21], v[144:145], 1, v[20:21]
	global_store_dwordx4 v[20:21], v[16:19], off sc1
.LBB0_2345:
	s_or_b64 exec, exec, s[22:23]
	s_nop 0
	v_add_u32_e32 v16, 0xb0, v155
	v_cmp_gt_i32_e32 vcc, s57, v16
	s_and_saveexec_b64 s[22:23], vcc
	s_cbranch_execz .LBB0_2347
	v_mul_f32_e32 v17, 0xbfb8aa3b, v12
	v_mul_f32_e32 v18, 0xbfb8aa3b, v13
	v_exp_f32_e32 v17, v17
	v_exp_f32_e32 v18, v18
	v_add_f32_e32 v17, 1.0, v17
	v_add_f32_e32 v19, 1.0, v18
	v_rcp_f32_e32 v18, v17
	v_rcp_f32_e32 v19, v19
	v_mul_f32_e32 v17, 0xbfb8aa3b, v14
	v_exp_f32_e32 v17, v17
	v_pk_mul_f32 v[12:13], v[12:13], v[18:19]
	v_mul_f32_e32 v18, 0xbfb8aa3b, v15
	v_exp_f32_e32 v18, v18
	v_pk_mul_f32 v[4:5], v[12:13], v[4:5]
	v_add_f32_e32 v12, 1.0, v17
	v_mul_f32_e32 v17, 0xbfb8aa3b, v8
	v_add_f32_e32 v13, 1.0, v18
	v_rcp_f32_e32 v12, v12
	v_rcp_f32_e32 v13, v13
	v_exp_f32_e32 v17, v17
	v_mul_f32_e32 v18, 0xbfb8aa3b, v9
	v_exp_f32_e32 v18, v18
	v_pk_mul_f32 v[12:13], v[14:15], v[12:13]
	v_add_f32_e32 v14, 1.0, v17
	v_mul_f32_e32 v17, 0xbfb8aa3b, v10
	v_add_f32_e32 v15, 1.0, v18
	v_exp_f32_e32 v17, v17
	v_mul_f32_e32 v18, 0xbfb8aa3b, v11
	v_exp_f32_e32 v19, v18
	v_rcp_f32_e32 v14, v14
	v_add_f32_e32 v17, 1.0, v17
	v_rcp_f32_e32 v15, v15
	v_rcp_f32_e32 v18, v17
	v_add_f32_e32 v17, 1.0, v19
	v_rcp_f32_e32 v19, v17
	v_pk_mul_f32 v[8:9], v[8:9], v[14:15]
	v_pk_mul_f32 v[6:7], v[12:13], v[6:7]
	v_pk_mul_f32 v[0:1], v[8:9], v[0:1]
	v_pk_mul_f32 v[8:9], v[10:11], v[18:19]
	s_nop 0
	v_pk_mul_f32 v[2:3], v[8:9], v[2:3]
	s_nop 0
	v_cvt_pk_bf16_f32 v3, v2, v3
	v_cvt_pk_bf16_f32 v2, v0, v1
	v_cvt_pk_bf16_f32 v0, v4, v5
	v_mov_b64_e32 v[4:5], s[8:9]
	v_mad_i64_i32 v[4:5], s[26:27], v16, s58, v[4:5]
	v_cvt_pk_bf16_f32 v1, v6, v7
	v_lshl_add_u64 v[4:5], v[144:145], 1, v[4:5]
	global_store_dwordx4 v[4:5], v[0:3], off sc1
